# P1_FR_port_conv_overlap
# speedup vs baseline: 1.0133x; 1.0133x over previous
; #define PG8_WAIT_V(n) asm volatile("s_waitcnt vmcnt(" #n ")" ::: "memory")
; #define PG8_BAR __builtin_amdgcn_s_barrier()
; template <class Epi, class Sched, bool ALIGN_EPI = false, bool SP2 = false>
; __device__ __forceinline__ void gemm_phase(PG8_LAS unsigned char* lds, const Gemm g, const Sched& S, const Epi& E) {
;     int tid_ = threadIdx.x; asm volatile("" : "+v"(tid_));
;     const int tid = tid_, wid = __builtin_amdgcn_readfirstlane(tid >> 6), lane = tid & 63, wr = wid >> 2, wc = wid & 3, fr = lane & 15, fq = lane >> 4;
;     const int K = g.K, nt = K / BK;
;     unsigned voffA[2], voffB[2];
; #pragma unroll
;     for (int i = 0; i < 2; ++i) { int R, C; stage_rc(tid * 16 + i * 8192, R, C); const int Rb = Epi::PERM ? ((R & ~31) + perm32(R & 31)) : R;
;         voffA[i] = (unsigned)(R * K + C) * 2u; voffB[i] = (unsigned)(Rb * K + C) * 2u; }
;     const size_t kstep = (size_t)(BK * 2);
;     const size_t hstep = (size_t)HALF * K * 2;
;     const size_t tstep = 2 * hstep;
;     const unsigned ldsw = (unsigned)wid * 1024u;
;     const int aoff = lds_byte(wr * 64 + fr, fq * 8), boff = lds_byte(wc * 32 + fr, fq * 8);
;     ...
;     Unit cur, nxt; int ui = 0;
;     if (!S.next(0, cur)) return;
;     f32x4 acc[2][2][4][2];
; #pragma unroll
;     for (int a = 0; a < 2; ++a)
; #pragma unroll
;         for (int b = 0; b < 2; ++b)
; #pragma unroll
;             for (int m = 0; m < 4; ++m)
; #pragma unroll
;                 for (int n = 0; n < 2; ++n) acc[a][b][m][n] = (f32x4){0.f, 0.f, 0.f, 0.f};
;     bf16x8 At[4][2], B0[2][2], B1[2][2];
;     const char* cA = (const char*)g.A + (size_t)cur.pm * tstep; const char* cB = (const char*)g.Bt + (size_t)cur.pn * tstep;
;     S.a_ready(cur);
;     if constexpr (SP2) {
;         PG8_STAGE(PG8_SB(0, 0), cB, voffB); PG8_STAGE(PG8_SB(0, 1), cB + hstep, voffB); PG8_STAGE(PG8_SA(0, 0), cA, voffA); PG8_STAGE(PG8_SA(0, 1), cA + hstep, voffA);
;         if (wr == 1) PG8_BAR;
;         PG8_WAIT_V(2); PG8_BAR;
;         PG8_STAGE(PG8_SB(1, 0), cB + kstep, voffB); PG8_STAGE(PG8_SA(1, 0), cA + kstep, voffA); PG8_STAGE(PG8_SB(1, 1), cB + hstep + kstep, voffB);
;         PG8_WAIT_V(6); PG8_BAR;
;     } else {
;         PG8_STAGE(PG8_SB(0, 0), cB, voffB); PG8_STAGE(PG8_SA(0, 0), cA, voffA); PG8_STAGE(PG8_SB(0, 1), cB + hstep, voffB); PG8_STAGE(PG8_SA(0, 1), cA + hstep, voffA);
;         if (wr == 1) PG8_BAR;
;         PG8_WAIT_V(4); PG8_BAR;
.LBB0_80:
	v_readlane_b32 s4, v244, 10
	v_readlane_b32 s5, v244, 11
	s_cmp_lt_i32 s4, 2
	s_cselect_b64 s[4:5], -1, 0
	s_add_u32 s6, s76, 0x1d00000
	s_addc_u32 s7, s77, 0
	v_writelane_b32 v244, s6, 29
	s_nop 1
	v_writelane_b32 v244, s7, 30
	s_add_u32 s6, s76, 0x2500000
	s_addc_u32 s7, s77, 0
	s_add_u32 s72, s76, 0x5100000
	s_addc_u32 s73, s77, 0
	s_add_u32 s60, s76, 0x6800000
	s_addc_u32 s61, s77, 0
	v_writelane_b32 v244, s6, 31
	s_add_u32 s84, s76, 0xa800000
	s_addc_u32 s85, s77, 0
	v_writelane_b32 v244, s7, 32
	s_and_b64 s[0:1], s[4:5], s[0:1]
	v_writelane_b32 v244, s0, 33
	s_andn2_b64 vcc, exec, s[0:1]
	s_nop 0
	v_writelane_b32 v244, s1, 34
	s_cbranch_vccnz .LBB0_154
	v_writelane_b32 v253, s4, 0
	v_writelane_b32 v253, s5, 1
	v_writelane_b32 v253, s6, 2
	v_writelane_b32 v253, s7, 3
	v_writelane_b32 v253, s8, 4
	v_writelane_b32 v253, s9, 5
	v_writelane_b32 v253, s10, 6
	v_writelane_b32 v253, s11, 7
	v_writelane_b32 v253, s12, 8
	v_writelane_b32 v253, s13, 9
	v_writelane_b32 v253, s14, 10
	v_writelane_b32 v253, s15, 11
	v_writelane_b32 v253, s16, 12
	v_writelane_b32 v253, s17, 13
	v_writelane_b32 v253, s18, 14
	v_writelane_b32 v253, s19, 15
	v_writelane_b32 v253, s20, 16
	v_writelane_b32 v253, s21, 17
	v_writelane_b32 v253, s22, 18
	v_writelane_b32 v253, s23, 19
	v_writelane_b32 v253, s24, 20
	v_writelane_b32 v253, s25, 21
	v_writelane_b32 v253, s26, 22
	v_writelane_b32 v253, s27, 23
	v_writelane_b32 v253, s28, 24
	v_writelane_b32 v253, s29, 25
	v_writelane_b32 v253, s30, 26
	v_writelane_b32 v253, s31, 27
	v_writelane_b32 v253, s32, 28
	v_writelane_b32 v253, s33, 29
	v_writelane_b32 v253, s34, 30
	v_writelane_b32 v253, s35, 31
	v_writelane_b32 v253, s36, 32
	v_writelane_b32 v253, s37, 33
	v_writelane_b32 v253, s38, 34
	v_writelane_b32 v253, s39, 35
	v_writelane_b32 v253, s40, 36
	v_writelane_b32 v253, s41, 37
	v_writelane_b32 v253, s42, 38
	v_writelane_b32 v253, s43, 39
	v_writelane_b32 v253, s44, 40
	v_writelane_b32 v253, s45, 41
	v_writelane_b32 v253, s46, 42
	v_writelane_b32 v253, s47, 43
	v_writelane_b32 v253, s48, 44
	v_writelane_b32 v253, s49, 45
	v_writelane_b32 v253, s50, 46
	v_writelane_b32 v253, s51, 47
	v_writelane_b32 v253, s52, 48
	v_writelane_b32 v253, s53, 49
	v_writelane_b32 v253, s54, 50
	v_writelane_b32 v253, s55, 51
	v_writelane_b32 v253, s56, 52
	v_writelane_b32 v253, s57, 53
	v_writelane_b32 v253, s58, 54
	v_writelane_b32 v253, s59, 55
	s_mov_b32 s40, vcc_lo
	s_mov_b32 s41, vcc_hi
	v_writelane_b32 v253, s40, 60
	v_writelane_b32 v253, s41, 61
	v_lshrrev_b32_e32 v254, 6, v185
	v_readlane_b32 s14, v244, 4
	v_readfirstlane_b32 s36, v254
	s_nop 3
	s_lshr_b32 s37, s36, 2
	s_and_b32 s38, s36, 3
	s_lshl_b32 s35, s36, 10
	s_add_u32 s10, s76, 0x6800000
	s_addc_u32 s11, s77, 0
	s_add_u32 s12, s76, 0x100000
	s_addc_u32 s13, s77, 0
	v_readlane_b32 s6, v244, 28
	s_lshl_b32 s7, s14, 3
	s_mov_b32 s16, 0
	s_mul_i32 s40, s16, s14
	s_add_u32 s40, s40, s2
	s_cmp_lt_u32 s40, 1792
	s_cselect_b32 s44, 1, 0
	s_min_u32 s40, s40, 1791
	s_and_b32 s41, s40, 7
	s_lshr_b32 s42, s40, 3
	s_mul_i32 s41, s41, 224
	s_add_u32 s41, s41, s42
	s_mul_hi_u32 s42, s41, 0x124924a
	s_mul_i32 s43, s42, 224
	s_sub_u32 s43, s41, s43
	s_and_b32 s40, s43, 7
	s_lshl_b32 s42, s42, 3
	s_add_u32 s17, s42, s40
	s_lshr_b32 s18, s43, 3
	s_cmp_eq_u32 s44, 0
	s_cbranch_scc1 .Lp1_exit
	v_and_b32_e32 v254, 63, v185
	v_and_b32_e32 v255, 15, v254
	v_lshrrev_b32_e32 v186, 1, v255
	v_lshrrev_b32_e32 v187, 4, v254
	v_xor_b32_e32 v186, v186, v187
	v_lshlrev_b32_e32 v255, 7, v255
	v_lshl_or_b32 v255, v186, 4, v255
	s_lshl_b32 s40, s37, 13
	s_lshl_b32 s41, s38, 12
	s_add_u32 s41, s41, 0x10000
	v_add_u32_e32 v245, s40, v255
	v_add_u32_e32 v247, s41, v255
	v_xor_b32_e32 v246, 64, v245
	v_xor_b32_e32 v248, 64, v247
	v_lshrrev_b32_e32 v255, 3, v254
	v_and_b32_e32 v186, 7, v254
	s_and_b32 s40, s36, 1
	s_lshl_b32 s40, s40, 2
	v_lshrrev_b32_e32 v187, 1, v255
	v_add_u32_e32 v187, s40, v187
	v_xor_b32_e32 v186, v186, v187
	v_lshlrev_b32_e32 v186, 4, v186
	s_lshl_b32 s40, s36, 3
	v_add_u32_e32 v187, s40, v255
	v_mul_u32_u24_e32 v187, 0x1000, v187
	v_add_u32_e32 v249, v187, v186
	v_add_u32_e32 v250, 0x40000, v249
	s_and_b32 s40, s36, 3
	s_lshl_b32 s40, s40, 3
	v_add_u32_e32 v187, s40, v255
	v_lshrrev_b32_e32 v254, 4, v187
	v_lshlrev_b32_e32 v254, 2, v254
	v_and_b32_e32 v255, 3, v187
	v_add_u32_e32 v254, v254, v255
	v_and_b32_e32 v187, 12, v187
	v_lshl_add_u32 v254, v187, 1, v254
	s_lshr_b32 s40, s36, 2
	s_lshl_b32 s40, s40, 5
	v_add_u32_e32 v254, s40, v254
	v_mul_u32_u24_e32 v254, 0x1000, v254
	v_add_u32_e32 v251, v254, v186
	v_add_u32_e32 v252, 0x40000, v251
	s_mul_i32 s40, s17, 0x100000
	s_add_u32 s22, s10, s40
	s_addc_u32 s23, s11, 0
	s_mul_i32 s40, s18, 0x100000
	s_add_u32 s24, s12, s40
	s_addc_u32 s25, s13, 0
	s_and_b32 s40, s16, 1
	s_lshl_b32 s4, s40, 8
	s_sub_u32 s4, 128, s4
	s_sub_u32 s5, 0, s40
	s_mul_i32 s8, s40, 3968
	s_add_u32 s30, s22, s8
	s_addc_u32 s31, s23, 0
	s_add_u32 s32, s24, s8
	s_addc_u32 s33, s25, 0
	s_add_u32 s56, s30, 0x80000
	s_addc_u32 s57, s31, 0
	s_add_u32 s58, s32, 0x80000
	s_addc_u32 s59, s33, 0
	s_add_i32 m0, s35, 0x0
	s_nop 0
	global_load_lds_dwordx4 v249, s[30:31]
	s_add_i32 m0, s35, 0x2000
	s_nop 0
	global_load_lds_dwordx4 v250, s[30:31]
	s_add_i32 m0, s35, 0x10000
	s_nop 0
	global_load_lds_dwordx4 v251, s[32:33]
	s_add_i32 m0, s35, 0x12000
	s_nop 0
	global_load_lds_dwordx4 v252, s[32:33]
	s_add_i32 m0, s35, 0x4000
	s_nop 0
	global_load_lds_dwordx4 v249, s[56:57]
	s_add_i32 m0, s35, 0x6000
	s_nop 0
	global_load_lds_dwordx4 v250, s[56:57]
	s_add_i32 m0, s35, 0x14000
	s_nop 0
	global_load_lds_dwordx4 v251, s[58:59]
	s_add_i32 m0, s35, 0x16000
	s_nop 0
	global_load_lds_dwordx4 v252, s[58:59]
	s_add_u32 s30, s30, s4
	s_addc_u32 s31, s31, s5
	s_add_u32 s56, s56, s4
	s_addc_u32 s57, s57, s5
	s_add_u32 s32, s32, s4
	s_addc_u32 s33, s33, s5
	s_add_u32 s58, s58, s4
	s_addc_u32 s59, s59, s5
	s_add_i32 m0, s35, 0x8000
	s_nop 0
	global_load_lds_dwordx4 v249, s[30:31]
	s_add_i32 m0, s35, 0xa000
	s_nop 0
	global_load_lds_dwordx4 v250, s[30:31]
	s_add_i32 m0, s35, 0x1c000
	s_nop 0
	global_load_lds_dwordx4 v251, s[58:59]
	s_add_i32 m0, s35, 0x1e000
	s_nop 0
	global_load_lds_dwordx4 v252, s[58:59]
	s_add_i32 m0, s35, 0xc000
	s_nop 0
	global_load_lds_dwordx4 v249, s[56:57]
	s_add_i32 m0, s35, 0xe000
	s_nop 0
	global_load_lds_dwordx4 v250, s[56:57]
	s_add_i32 m0, s35, 0x18000
	s_nop 0
	global_load_lds_dwordx4 v251, s[32:33]
	s_add_i32 m0, s35, 0x1a000
	s_nop 0
	global_load_lds_dwordx4 v252, s[32:33]
	s_add_u32 s30, s30, s4
	s_addc_u32 s31, s31, s5
	s_add_u32 s56, s56, s4
	s_addc_u32 s57, s57, s5
	s_add_u32 s32, s32, s4
	s_addc_u32 s33, s33, s5
	s_add_u32 s58, s58, s4
	s_addc_u32 s59, s59, s5
	s_waitcnt vmcnt(12)
	s_barrier
; #define PG8_STAGE(bufoff, gbase, voff) do { _Pragma("unroll") for (int _i = 0; _i < 2; ++_i) \
;         __builtin_amdgcn_global_load_lds((const unsigned*)((const char*)(gbase) + (voff)[_i]), (PG8_LAS unsigned*)(lds + (bufoff) + ldsw + _i * 8192), 16, 0, 0); } while (0)
; #define PG8_LDA(dst, b, h) do { _Pragma("unroll") for (int m = 0; m < 4; ++m) _Pragma("unroll") for (int k = 0; k < 2; ++k) dst[m][k] = *(const PG8_LAS bf16x8*)(lds + PG8_SA(b, h) + aoff + m * 2048 + k * 1024); } while (0)
; #define PG8_LDB(dst, b, h) do { _Pragma("unroll") for (int n = 0; n < 2; ++n) _Pragma("unroll") for (int k = 0; k < 2; ++k) dst[n][k] = *(const PG8_LAS bf16x8*)(lds + PG8_SB(b, h) + boff + n * 2048 + k * 1024); } while (0)
; #define PG8_SCHED __builtin_amdgcn_sched_barrier(0)
; template <class Epi, class Sched, bool ALIGN_EPI = false, bool SP2 = false>
; __device__ __forceinline__ void gemm_phase(PG8_LAS unsigned char* lds, const Gemm g, const Sched& S, const Epi& E) {
;     ...
;     for (;;) {
;         const bool has_next = S.next(ui + 1, nxt);
;         const char* nA = has_next ? (const char*)g.A + (size_t)nxt.pm * tstep : cA; const char* nB = has_next ? (const char*)g.Bt + (size_t)nxt.pn * tstep : cB;
;         for (int t = 0; t < nt; t += 2) {
;             const bool last = (t == nt - 2);
;             const char* a1 = cA + (size_t)(t + 1) * kstep;
;             const char* a2 = last ? nA : cA + (size_t)(t + 2) * kstep; const char* b2 = last ? nB : cB + (size_t)(t + 2) * kstep;
;             const char* a3 = a2 + kstep; const char* b3 = b2 + kstep;
;             if (last && has_next) S.a_ready(nxt);
;             if constexpr (SP2) {
;             PG8_LDB(B0, 0, 0); PG8_LDB(B1, 0, 1); PG8_SCHED; PG8_LDA(At, 0, 0); PG8_STAGE(PG8_SA(1, 1), a1 + hstep, voffA);
;     ...
; #pragma unroll
;         for (int a = 0; a < 2; ++a)
; #pragma unroll
;             for (int b = 0; b < 2; ++b)
; #pragma unroll
;                 for (int m = 0; m < 4; ++m)
; #pragma unroll
;                     for (int n = 0; n < 2; ++n) acc[a][b][m][n] = (f32x4){0.f, 0.f, 0.f, 0.f};
.Lp1_unit:
	s_add_u32 s45, s16, 1
	s_mul_i32 s40, s45, s14
	s_add_u32 s40, s40, s2
	s_cmp_lt_u32 s40, 1792
	s_cselect_b32 s19, 1, 0
	s_min_u32 s40, s40, 1791
	s_and_b32 s41, s40, 7
	s_lshr_b32 s42, s40, 3
	s_mul_i32 s41, s41, 224
	s_add_u32 s41, s41, s42
	s_mul_hi_u32 s42, s41, 0x124924a
	s_mul_i32 s43, s42, 224
	s_sub_u32 s43, s41, s43
	s_and_b32 s40, s43, 7
	s_lshl_b32 s42, s42, 3
	s_add_u32 s20, s42, s40
	s_lshr_b32 s21, s43, 3
	s_mul_i32 s40, s20, 0x100000
	s_add_u32 s26, s10, s40
	s_addc_u32 s27, s11, 0
	s_mul_i32 s40, s21, 0x100000
	s_add_u32 s28, s12, s40
	s_addc_u32 s29, s13, 0
	s_cmp_eq_u32 s19, 0
	s_cselect_b32 s26, s22, s26
	s_cselect_b32 s27, s23, s27
	s_cselect_b32 s28, s24, s28
	s_cselect_b32 s29, s25, s29
	s_add_u32 s30, s22, s8
	s_addc_u32 s31, s23, 0
	s_add_u32 s32, s24, s8
	s_addc_u32 s33, s25, 0
	s_add_u32 s30, s30, s4
	s_addc_u32 s31, s31, s5
	s_add_u32 s32, s32, s4
	s_addc_u32 s33, s33, s5
	s_add_u32 s30, s30, s4
	s_addc_u32 s31, s31, s5
	s_add_u32 s32, s32, s4
	s_addc_u32 s33, s33, s5
	s_add_u32 s56, s30, 0x80000
	s_addc_u32 s57, s31, 0
	s_add_u32 s58, s32, 0x80000
	s_addc_u32 s59, s33, 0
	s_movk_i32 s34, 16
	v_mov_b32_e32 v0, 0
	v_mov_b32_e32 v1, 0
	v_mov_b32_e32 v2, 0
	v_mov_b32_e32 v3, 0
	v_mov_b32_e32 v4, 0
	v_mov_b32_e32 v5, 0
	v_mov_b32_e32 v6, 0
	v_mov_b32_e32 v7, 0
	v_mov_b32_e32 v8, 0
	v_mov_b32_e32 v9, 0
	v_mov_b32_e32 v10, 0
	v_mov_b32_e32 v11, 0
	v_mov_b32_e32 v12, 0
	v_mov_b32_e32 v13, 0
	v_mov_b32_e32 v14, 0
	v_mov_b32_e32 v15, 0
	v_mov_b32_e32 v16, 0
	v_mov_b32_e32 v17, 0
	v_mov_b32_e32 v18, 0
	v_mov_b32_e32 v19, 0
	v_mov_b32_e32 v20, 0
	v_mov_b32_e32 v21, 0
	v_mov_b32_e32 v22, 0
	v_mov_b32_e32 v23, 0
	v_mov_b32_e32 v24, 0
	v_mov_b32_e32 v25, 0
	v_mov_b32_e32 v26, 0
	v_mov_b32_e32 v27, 0
	v_mov_b32_e32 v28, 0
	v_mov_b32_e32 v29, 0
	v_mov_b32_e32 v30, 0
	v_mov_b32_e32 v31, 0
	v_mov_b32_e32 v32, 0
	v_mov_b32_e32 v33, 0
	v_mov_b32_e32 v34, 0
	v_mov_b32_e32 v35, 0
	v_mov_b32_e32 v36, 0
	v_mov_b32_e32 v37, 0
	v_mov_b32_e32 v38, 0
	v_mov_b32_e32 v39, 0
	v_mov_b32_e32 v40, 0
	v_mov_b32_e32 v41, 0
	v_mov_b32_e32 v42, 0
	v_mov_b32_e32 v43, 0
	v_mov_b32_e32 v44, 0
	v_mov_b32_e32 v45, 0
	v_mov_b32_e32 v46, 0
	v_mov_b32_e32 v47, 0
	v_mov_b32_e32 v48, 0
	v_mov_b32_e32 v49, 0
	v_mov_b32_e32 v50, 0
	v_mov_b32_e32 v51, 0
	v_mov_b32_e32 v52, 0
	v_mov_b32_e32 v53, 0
	v_mov_b32_e32 v54, 0
	v_mov_b32_e32 v55, 0
	v_mov_b32_e32 v56, 0
	v_mov_b32_e32 v57, 0
	v_mov_b32_e32 v58, 0
	v_mov_b32_e32 v59, 0
	v_mov_b32_e32 v60, 0
	v_mov_b32_e32 v61, 0
	v_mov_b32_e32 v62, 0
	v_mov_b32_e32 v63, 0
	v_mov_b32_e32 v64, 0
	v_mov_b32_e32 v65, 0
	v_mov_b32_e32 v66, 0
	v_mov_b32_e32 v67, 0
	v_mov_b32_e32 v68, 0
	v_mov_b32_e32 v69, 0
	v_mov_b32_e32 v70, 0
	v_mov_b32_e32 v71, 0
	v_mov_b32_e32 v72, 0
	v_mov_b32_e32 v73, 0
	v_mov_b32_e32 v74, 0
	v_mov_b32_e32 v75, 0
	v_mov_b32_e32 v76, 0
	v_mov_b32_e32 v77, 0
	v_mov_b32_e32 v78, 0
	v_mov_b32_e32 v79, 0
	v_mov_b32_e32 v80, 0
	v_mov_b32_e32 v81, 0
	v_mov_b32_e32 v82, 0
	v_mov_b32_e32 v83, 0
	v_mov_b32_e32 v84, 0
	v_mov_b32_e32 v85, 0
	v_mov_b32_e32 v86, 0
	v_mov_b32_e32 v87, 0
	v_mov_b32_e32 v88, 0
	v_mov_b32_e32 v89, 0
	v_mov_b32_e32 v90, 0
	v_mov_b32_e32 v91, 0
	v_mov_b32_e32 v92, 0
	v_mov_b32_e32 v93, 0
	v_mov_b32_e32 v94, 0
	v_mov_b32_e32 v95, 0
	v_mov_b32_e32 v96, 0
	v_mov_b32_e32 v97, 0
	v_mov_b32_e32 v98, 0
	v_mov_b32_e32 v99, 0
	v_mov_b32_e32 v100, 0
	v_mov_b32_e32 v101, 0
	v_mov_b32_e32 v102, 0
	v_mov_b32_e32 v103, 0
	v_mov_b32_e32 v104, 0
	v_mov_b32_e32 v105, 0
	v_mov_b32_e32 v106, 0
	v_mov_b32_e32 v107, 0
	v_mov_b32_e32 v108, 0
	v_mov_b32_e32 v109, 0
	v_mov_b32_e32 v110, 0
	v_mov_b32_e32 v111, 0
	v_mov_b32_e32 v112, 0
	v_mov_b32_e32 v113, 0
	v_mov_b32_e32 v114, 0
	v_mov_b32_e32 v115, 0
	v_mov_b32_e32 v116, 0
	v_mov_b32_e32 v117, 0
	v_mov_b32_e32 v118, 0
	v_mov_b32_e32 v119, 0
	v_mov_b32_e32 v120, 0
	v_mov_b32_e32 v121, 0
	v_mov_b32_e32 v122, 0
	v_mov_b32_e32 v123, 0
	v_mov_b32_e32 v124, 0
	v_mov_b32_e32 v125, 0
	v_mov_b32_e32 v126, 0
	v_mov_b32_e32 v127, 0
	ds_read_b128 v[196:199], v247 offset:0
	ds_read_b128 v[200:203], v248 offset:0
	ds_read_b128 v[204:207], v247 offset:2048
	ds_read_b128 v[208:211], v248 offset:2048
	ds_read_b128 v[128:131], v245 offset:0
	ds_read_b128 v[132:135], v246 offset:0
	ds_read_b128 v[136:139], v245 offset:2048
	ds_read_b128 v[140:143], v246 offset:2048
	ds_read_b128 v[144:147], v245 offset:4096
	ds_read_b128 v[148:151], v246 offset:4096
	ds_read_b128 v[152:155], v245 offset:6144
	ds_read_b128 v[156:159], v246 offset:6144
	s_cmp_ge_u32 s36, 4
	s_cbranch_scc1 .Lp1_kloop1

; __device__ __forceinline__ void p0_transpose_item(const float* __restrict__ W, int K, int N, bf16* __restrict__ WT, int mode, const float* __restrict__ kscale, int item, int lane) {
;     const int nblk = N / 64, kb = item / nblk, nb = item % nblk, k0 = 64 * kb, n0 = 64 * nb;
;     const float* src = W + (size_t)k0 * N + n0 + lane;
;     float v[64];
; #pragma unroll
;     for (int i = 0; i < 64; ++i) v[i] = src[(size_t)i * N];
;     if (kscale) {
; #pragma unroll
;         for (int i = 0; i < 64; ++i) v[i] *= kscale[k0 + i]; }
;     const int rbase = (mode == 0) ? n0 : (256 * (n0 >> 7) + (n0 & 127) + (mode == 2 ? 128 : 0));
;     bf16* dst = WT + (size_t)(rbase + lane) * K + k0;
;     __device__ __forceinline__ void convert(int r, int lane) const {
;         if (r < I_OUT) { p0_transpose_item(w_out, DM, DM, Wout_t, 0, nullptr, r, lane); return; } r -= I_OUT;
;         if (r < I_G) { p0_transpose_item(w_gate, DM, FF, Wgu_t, 1, kscale, r, lane); return; } r -= I_G;
;         if (r < I_G) { p0_transpose_item(w_up, DM, FF, Wgu_t, 2, kscale, r, lane); return; } r -= I_G;
;         p0_transpose_item(w_down, FF, DM, Wdn_t, 0, nullptr, r, lane);
;     }
;     __device__ __forceinline__ void done(const pg8::Unit&) const {
;         if (nxt < NITEMS) { convert(nxt, (int)(threadIdx.x & 63)); nxt += ngw; }
.Lp1_kdone:
	s_waitcnt lgkmcnt(0)
	s_nop 7
	s_nop 7
	s_cmp_lt_u32 s6, 9472
	s_cselect_b32 s39, 1, 0
	s_cbranch_scc0 .Lp1_cv_skip_u
	s_mov_b32 s40, s6
	s_cmp_lt_u32 s40, 1024
	s_cbranch_scc1 .Lp1_cv_out_u
	s_sub_u32 s40, s40, 1024
	s_cmp_lt_u32 s40, 2816
	s_cbranch_scc1 .Lp1_cv_gate_u
	s_sub_u32 s40, s40, 2816
	s_cmp_lt_u32 s40, 2816
	s_cbranch_scc1 .Lp1_cv_up_u
	s_sub_u32 s40, s40, 2816
	v_readlane_b32 s48, v244, 26
	v_readlane_b32 s49, v244, 27
	s_movk_i32 s41, 2048
	s_movk_i32 s42, 5632
	s_mov_b32 s43, 0x5100000
	s_mov_b32 s9, 0
	s_branch .Lp1_cv_dec_u
.Lp1_cv_out_u:
	v_readlane_b32 s48, v244, 18
	v_readlane_b32 s49, v244, 19
	s_movk_i32 s41, 2048
	s_movk_i32 s42, 2048
	s_mov_b32 s43, 0x1d00000
	s_mov_b32 s9, 0
	s_branch .Lp1_cv_dec_u
.Lp1_cv_gate_u:
	v_readlane_b32 s48, v244, 22
	v_readlane_b32 s49, v244, 23
	s_mov_b32 s9, 1
	s_branch .Lp1_cv_gu_u
.Lp1_cv_up_u:
	v_readlane_b32 s48, v244, 24
	v_readlane_b32 s49, v244, 25
	s_mov_b32 s9, 2
.Lp1_cv_gu_u:
	s_movk_i32 s41, 5632
	s_movk_i32 s42, 2048
	s_mov_b32 s43, 0x2500000
.Lp1_cv_dec_u:
	s_nop 3
	s_cmp_eq_u32 s41, 2048
	s_cbranch_scc0 .Lp1_cv_d88_u
	s_lshr_b32 s44, s40, 5
	s_and_b32 s45, s40, 31
	s_branch .Lp1_cv_dd_u
.Lp1_cv_d88_u:
	s_mul_hi_u32 s44, s40, 0x2e8ba2f
	s_mul_i32 s45, s44, 88
	s_sub_u32 s45, s40, s45
.Lp1_cv_dd_u:
	s_lshl_b32 s44, s44, 6
	s_lshl_b32 s45, s45, 6
	s_mul_i32 s40, s44, s41
	s_add_u32 s40, s40, s45
	s_lshl_b32 s46, s41, 2
	s_mul_hi_u32 s47, s40, 4
	s_lshl_b32 s40, s40, 2
	s_add_u32 s48, s48, s40
	s_addc_u32 s49, s49, s47
	v_readlane_b32 s54, v244, 20
	v_readlane_b32 s55, v244, 21
	s_lshr_b32 s40, s45, 7
	s_lshl_b32 s40, s40, 8
	s_and_b32 s47, s45, 127
	s_add_u32 s40, s40, s47
	s_cmp_eq_u32 s9, 2
	s_cselect_b32 s47, 128, 0
	s_add_u32 s40, s40, s47
	s_cmp_eq_u32 s9, 0
	s_cselect_b32 s40, s45, s40
	s_mul_i32 s40, s40, s42
	s_add_u32 s40, s40, s44
	s_lshl_b32 s40, s40, 1
	s_add_u32 s52, s76, s43
	s_addc_u32 s53, s77, 0
	s_add_u32 s52, s52, s40
	s_addc_u32 s53, s53, 0
	v_and_b32_e32 v198, 63, v185
	v_lshlrev_b32_e32 v196, 2, v198
	s_lshl_b32 s42, s42, 1
	v_mul_lo_u32 v198, v198, s42
	s_lshl_b32 s44, s44, 2
	s_add_u32 s54, s54, s44
	s_addc_u32 s55, s55, 0
	s_cmp_eq_u32 s9, 0
	s_cbranch_scc1 .Lp1_cv_noks_u
	global_load_dword v197, v196, s[54:55]
.Lp1_cv_noks_u:
	global_load_dword v128, v196, s[48:49]
	s_add_u32 s48, s48, s46
	s_addc_u32 s49, s49, 0
	global_load_dword v129, v196, s[48:49]
	s_add_u32 s48, s48, s46
	s_addc_u32 s49, s49, 0
	global_load_dword v130, v196, s[48:49]
	s_add_u32 s48, s48, s46
	s_addc_u32 s49, s49, 0
	global_load_dword v131, v196, s[48:49]
	s_add_u32 s48, s48, s46
	s_addc_u32 s49, s49, 0
	global_load_dword v132, v196, s[48:49]
	s_add_u32 s48, s48, s46
	s_addc_u32 s49, s49, 0
	global_load_dword v133, v196, s[48:49]
	s_add_u32 s48, s48, s46
	s_addc_u32 s49, s49, 0
	global_load_dword v134, v196, s[48:49]
	s_add_u32 s48, s48, s46
	s_addc_u32 s49, s49, 0
	global_load_dword v135, v196, s[48:49]
	s_add_u32 s48, s48, s46
	s_addc_u32 s49, s49, 0
	global_load_dword v136, v196, s[48:49]
	s_add_u32 s48, s48, s46
	s_addc_u32 s49, s49, 0
	global_load_dword v137, v196, s[48:49]
	s_add_u32 s48, s48, s46
	s_addc_u32 s49, s49, 0
	global_load_dword v138, v196, s[48:49]
	s_add_u32 s48, s48, s46
	s_addc_u32 s49, s49, 0
	global_load_dword v139, v196, s[48:49]
	s_add_u32 s48, s48, s46
	s_addc_u32 s49, s49, 0
	global_load_dword v140, v196, s[48:49]
	s_add_u32 s48, s48, s46
	s_addc_u32 s49, s49, 0
	global_load_dword v141, v196, s[48:49]
	s_add_u32 s48, s48, s46
	s_addc_u32 s49, s49, 0
	global_load_dword v142, v196, s[48:49]
	s_add_u32 s48, s48, s46
	s_addc_u32 s49, s49, 0
	global_load_dword v143, v196, s[48:49]
	s_add_u32 s48, s48, s46
	s_addc_u32 s49, s49, 0
	global_load_dword v144, v196, s[48:49]
	s_add_u32 s48, s48, s46
	s_addc_u32 s49, s49, 0
	global_load_dword v145, v196, s[48:49]
	s_add_u32 s48, s48, s46
	s_addc_u32 s49, s49, 0
	global_load_dword v146, v196, s[48:49]
	s_add_u32 s48, s48, s46
	s_addc_u32 s49, s49, 0
	global_load_dword v147, v196, s[48:49]
	s_add_u32 s48, s48, s46
	s_addc_u32 s49, s49, 0
	global_load_dword v148, v196, s[48:49]
	s_add_u32 s48, s48, s46
	s_addc_u32 s49, s49, 0
	global_load_dword v149, v196, s[48:49]
	s_add_u32 s48, s48, s46
	s_addc_u32 s49, s49, 0
	global_load_dword v150, v196, s[48:49]
	s_add_u32 s48, s48, s46
	s_addc_u32 s49, s49, 0
	global_load_dword v151, v196, s[48:49]
	s_add_u32 s48, s48, s46
	s_addc_u32 s49, s49, 0
	global_load_dword v152, v196, s[48:49]
	s_add_u32 s48, s48, s46
	s_addc_u32 s49, s49, 0
	global_load_dword v153, v196, s[48:49]
	s_add_u32 s48, s48, s46
	s_addc_u32 s49, s49, 0
	global_load_dword v154, v196, s[48:49]
	s_add_u32 s48, s48, s46
	s_addc_u32 s49, s49, 0
	global_load_dword v155, v196, s[48:49]
	s_add_u32 s48, s48, s46
	s_addc_u32 s49, s49, 0
	global_load_dword v156, v196, s[48:49]
	s_add_u32 s48, s48, s46
	s_addc_u32 s49, s49, 0
	global_load_dword v157, v196, s[48:49]
	s_add_u32 s48, s48, s46
	s_addc_u32 s49, s49, 0
	global_load_dword v158, v196, s[48:49]
	s_add_u32 s48, s48, s46
	s_addc_u32 s49, s49, 0
	global_load_dword v159, v196, s[48:49]
	s_add_u32 s48, s48, s46
	s_addc_u32 s49, s49, 0
	global_load_dword v160, v196, s[48:49]
	s_add_u32 s48, s48, s46
	s_addc_u32 s49, s49, 0
	global_load_dword v161, v196, s[48:49]
	s_add_u32 s48, s48, s46
	s_addc_u32 s49, s49, 0
	global_load_dword v162, v196, s[48:49]
	s_add_u32 s48, s48, s46
	s_addc_u32 s49, s49, 0
	global_load_dword v163, v196, s[48:49]
	s_add_u32 s48, s48, s46
	s_addc_u32 s49, s49, 0
	global_load_dword v164, v196, s[48:49]
	s_add_u32 s48, s48, s46
	s_addc_u32 s49, s49, 0
	global_load_dword v165, v196, s[48:49]
	s_add_u32 s48, s48, s46
;     __device__ __forceinline__ void operator()(const f32x4 (&acc)[2][2][4][2], const Unit& u, int wr, int wc, int fr, int fq) const {
;         const int row0 = u.pm * BM + wr * 64 + fr, col0 = u.pn * BM + wc * 32 + 8 * fq;
;         const int mode = (u.pn >= 12 && u.pn < 16) ? 1 : ((u.pn >= 16 && u.pn < 20) ? 2 : 0);
;         float lg = 0.f; if (mode) { const int hd = (u.pn - 12) & 3; lg = __log2f(1.0f - __builtin_amdgcn_exp2f(-5.0f - (float)hd)); }
; #pragma unroll
;         for (int ai = 0; ai < 2; ++ai)
; #pragma unroll
;             for (int m = 0; m < 4; ++m) { const int row = row0 + ai * HALF + m * 16; bf16_t* rowp = O + (size_t)row * ldc + col0;
;                 float sc = 1.f;
;                 if (mode) { const float e = (float)((row & 2047) - 1024) * lg; sc = (mode == 1) ? __builtin_amdgcn_exp2f(e) : __builtin_amdgcn_exp2f(-e) * 0.0625f; }
; __device__ __forceinline__ void p0_transpose_item(const float* __restrict__ W, int K, int N, bf16* __restrict__ WT, int mode, const float* __restrict__ kscale, int item, int lane) {
;     ...
;     const float* src = W + (size_t)k0 * N + n0 + lane;
;     float v[64];
; #pragma unroll
;     for (int i = 0; i < 64; ++i) v[i] = src[(size_t)i * N];
	s_addc_u32 s49, s49, 0
	global_load_dword v166, v196, s[48:49]
	s_add_u32 s48, s48, s46
	s_addc_u32 s49, s49, 0
	global_load_dword v167, v196, s[48:49]
	s_add_u32 s48, s48, s46
	s_addc_u32 s49, s49, 0
	global_load_dword v168, v196, s[48:49]
	s_add_u32 s48, s48, s46
	s_addc_u32 s49, s49, 0
	global_load_dword v169, v196, s[48:49]
	s_add_u32 s48, s48, s46
	s_addc_u32 s49, s49, 0
	global_load_dword v170, v196, s[48:49]
	s_add_u32 s48, s48, s46
	s_addc_u32 s49, s49, 0
	global_load_dword v171, v196, s[48:49]
	s_add_u32 s48, s48, s46
	s_addc_u32 s49, s49, 0
	global_load_dword v172, v196, s[48:49]
	s_add_u32 s48, s48, s46
	s_addc_u32 s49, s49, 0
	global_load_dword v173, v196, s[48:49]
	s_add_u32 s48, s48, s46
	s_addc_u32 s49, s49, 0
	global_load_dword v174, v196, s[48:49]
	s_add_u32 s48, s48, s46
	s_addc_u32 s49, s49, 0
	global_load_dword v175, v196, s[48:49]
	s_add_u32 s48, s48, s46
	s_addc_u32 s49, s49, 0
	global_load_dword v176, v196, s[48:49]
	s_add_u32 s48, s48, s46
	s_addc_u32 s49, s49, 0
	global_load_dword v177, v196, s[48:49]
	s_add_u32 s48, s48, s46
	s_addc_u32 s49, s49, 0
	global_load_dword v178, v196, s[48:49]
	s_add_u32 s48, s48, s46
	s_addc_u32 s49, s49, 0
	global_load_dword v179, v196, s[48:49]
	s_add_u32 s48, s48, s46
	s_addc_u32 s49, s49, 0
	global_load_dword v180, v196, s[48:49]
	s_add_u32 s48, s48, s46
	s_addc_u32 s49, s49, 0
	global_load_dword v181, v196, s[48:49]
	s_add_u32 s48, s48, s46
	s_addc_u32 s49, s49, 0
	global_load_dword v182, v196, s[48:49]
	s_add_u32 s48, s48, s46
	s_addc_u32 s49, s49, 0
	global_load_dword v183, v196, s[48:49]
	s_add_u32 s48, s48, s46
	s_addc_u32 s49, s49, 0
	global_load_dword v188, v196, s[48:49]
	s_add_u32 s48, s48, s46
	s_addc_u32 s49, s49, 0
	global_load_dword v189, v196, s[48:49]
	s_add_u32 s48, s48, s46
	s_addc_u32 s49, s49, 0
	global_load_dword v190, v196, s[48:49]
	s_add_u32 s48, s48, s46
	s_addc_u32 s49, s49, 0
	global_load_dword v191, v196, s[48:49]
	s_add_u32 s48, s48, s46
	s_addc_u32 s49, s49, 0
	global_load_dword v192, v196, s[48:49]
	s_add_u32 s48, s48, s46
	s_addc_u32 s49, s49, 0
	global_load_dword v193, v196, s[48:49]
	s_add_u32 s48, s48, s46
	s_addc_u32 s49, s49, 0
	global_load_dword v194, v196, s[48:49]
	s_add_u32 s48, s48, s46
	s_addc_u32 s49, s49, 0
	global_load_dword v195, v196, s[48:49]
.Lp1_cv_skip_u:
	v_and_b32_e32 v254, 63, v185
	v_and_b32_e32 v255, 15, v254
	v_lshrrev_b32_e32 v186, 4, v254
	s_lshl_b32 s40, s37, 6
	v_add_u32_e32 v255, s40, v255
	v_mul_u32_u24_e32 v204, 0x3800, v255
	s_lshl_b32 s41, s38, 6
	v_lshl_add_u32 v204, v186, 4, v204
	v_add_u32_e32 v204, s41, v204
	s_and_b32 s42, s17, 7
	s_lshl_b32 s42, s42, 8
	s_sub_u32 s42, s42, 1024
	v_add_u32_e32 v209, s42, v255
	s_mul_i32 s40, s17, 0x380000
	s_lshl_b32 s41, s18, 9
	s_add_u32 s40, s40, s41
	s_add_u32 s50, s76, 0xa800000
	s_addc_u32 s51, s77, 0
	s_add_u32 s50, s50, s40
	s_addc_u32 s51, s51, 0
	s_sub_u32 s40, s18, 12
	s_cmp_lt_u32 s40, 8
	s_cbranch_scc0 .Lp1_ep_plain
	s_and_b32 s41, s40, 3
	v_cvt_f32_ubyte0_e32 v208, s41
	v_sub_f32_e32 v208, 0xc0a00000, v208
	v_exp_f32_e32 v208, v208
	s_nop 0
	v_sub_f32_e32 v208, 1.0, v208
	v_log_f32_e32 v208, v208
	s_cmp_lt_u32 s40, 4
	s_cbranch_scc0 .Lp1_ep_mode2
	v_add_u32_e32 v205, 0x0, v204
	v_add_u32_e32 v206, 0, v209
	v_cvt_f32_i32_e32 v206, v206
	v_mul_f32_e32 v206, v208, v206
	v_exp_f32_e32 v207, v206
	s_nop 0
	v_mul_f32_e32 v0, v0, v207
	v_mul_f32_e32 v1, v1, v207
	v_mul_f32_e32 v2, v2, v207
	v_mul_f32_e32 v3, v3, v207
	v_mul_f32_e32 v4, v4, v207
	v_mul_f32_e32 v5, v5, v207
	v_mul_f32_e32 v6, v6, v207
	v_mul_f32_e32 v7, v7, v207
	v_cvt_pk_bf16_f32 v212, v0, v1
	v_cvt_pk_bf16_f32 v213, v2, v3
	v_cvt_pk_bf16_f32 v214, v4, v5
	v_cvt_pk_bf16_f32 v215, v6, v7
	s_nop 1
	global_store_dwordx4 v205, v[212:215], s[50:51] offset:0
	s_nop 1
	v_mul_f32_e32 v32, v32, v207
	v_mul_f32_e32 v33, v33, v207
	v_mul_f32_e32 v34, v34, v207
	v_mul_f32_e32 v35, v35, v207
	v_mul_f32_e32 v36, v36, v207
	v_mul_f32_e32 v37, v37, v207
	v_mul_f32_e32 v38, v38, v207
	v_mul_f32_e32 v39, v39, v207
	v_cvt_pk_bf16_f32 v212, v32, v33
	v_cvt_pk_bf16_f32 v213, v34, v35
	v_cvt_pk_bf16_f32 v214, v36, v37
	v_cvt_pk_bf16_f32 v215, v38, v39
	s_nop 1
	global_store_dwordx4 v205, v[212:215], s[50:51] offset:256
	s_nop 1
	v_add_u32_e32 v205, 0x38000, v204
	v_add_u32_e32 v206, 16, v209
	v_cvt_f32_i32_e32 v206, v206
	v_mul_f32_e32 v206, v208, v206
	v_exp_f32_e32 v207, v206
	s_nop 0
	v_mul_f32_e32 v8, v8, v207
	v_mul_f32_e32 v9, v9, v207
	v_mul_f32_e32 v10, v10, v207
	v_mul_f32_e32 v11, v11, v207
	v_mul_f32_e32 v12, v12, v207
	v_mul_f32_e32 v13, v13, v207
	v_mul_f32_e32 v14, v14, v207
	v_mul_f32_e32 v15, v15, v207
	v_cvt_pk_bf16_f32 v212, v8, v9
	v_cvt_pk_bf16_f32 v213, v10, v11
	v_cvt_pk_bf16_f32 v214, v12, v13
	v_cvt_pk_bf16_f32 v215, v14, v15
	s_nop 1
	global_store_dwordx4 v205, v[212:215], s[50:51] offset:0
	s_nop 1
	v_mul_f32_e32 v40, v40, v207
	v_mul_f32_e32 v41, v41, v207
	v_mul_f32_e32 v42, v42, v207
	v_mul_f32_e32 v43, v43, v207
	v_mul_f32_e32 v44, v44, v207
	v_mul_f32_e32 v45, v45, v207
	v_mul_f32_e32 v46, v46, v207
	v_mul_f32_e32 v47, v47, v207
	v_cvt_pk_bf16_f32 v212, v40, v41
	v_cvt_pk_bf16_f32 v213, v42, v43
	v_cvt_pk_bf16_f32 v214, v44, v45
	v_cvt_pk_bf16_f32 v215, v46, v47
	s_nop 1
	global_store_dwordx4 v205, v[212:215], s[50:51] offset:256
	s_nop 1
	v_add_u32_e32 v205, 0x70000, v204
	v_add_u32_e32 v206, 32, v209
	v_cvt_f32_i32_e32 v206, v206
	v_mul_f32_e32 v206, v208, v206
	v_exp_f32_e32 v207, v206
	s_nop 0
	v_mul_f32_e32 v16, v16, v207
	v_mul_f32_e32 v17, v17, v207
	v_mul_f32_e32 v18, v18, v207
	v_mul_f32_e32 v19, v19, v207
	v_mul_f32_e32 v20, v20, v207
	v_mul_f32_e32 v21, v21, v207
	v_mul_f32_e32 v22, v22, v207
; __device__ __forceinline__ unsigned cvt_pk_bf16(float lo, float hi) { unsigned r; asm volatile("v_cvt_pk_bf16_f32 %0, %1, %2" : "=v"(r) : "v"(lo), "v"(hi)); return r; }
;     __device__ __forceinline__ void operator()(const f32x4 (&acc)[2][2][4][2], const Unit& u, int wr, int wc, int fr, int fq) const {
;     ...
;         for (int ai = 0; ai < 2; ++ai)
; #pragma unroll
;             for (int m = 0; m < 4; ++m) { const int row = row0 + ai * HALF + m * 16; bf16_t* rowp = O + (size_t)row * ldc + col0;
;                 float sc = 1.f;
;                 if (mode) { const float e = (float)((row & 2047) - 1024) * lg; sc = (mode == 1) ? __builtin_amdgcn_exp2f(e) : __builtin_amdgcn_exp2f(-e) * 0.0625f; }
; #pragma unroll
;                 for (int bj = 0; bj < 2; ++bj) { const f32x4 v0 = acc[ai][bj][m][0] * sc, v1 = acc[ai][bj][m][1] * sc;
;                     u32x4 w; w.x = cvt_pk_bf16(v0[0], v0[1]); w.y = cvt_pk_bf16(v0[2], v0[3]); w.z = cvt_pk_bf16(v1[0], v1[1]); w.w = cvt_pk_bf16(v1[2], v1[3]);
;                     *(u32x4*)(rowp + bj * HALF) = w; } }
	v_mul_f32_e32 v23, v23, v207
	v_cvt_pk_bf16_f32 v212, v16, v17
	v_cvt_pk_bf16_f32 v213, v18, v19
	v_cvt_pk_bf16_f32 v214, v20, v21
	v_cvt_pk_bf16_f32 v215, v22, v23
	s_nop 1
	global_store_dwordx4 v205, v[212:215], s[50:51] offset:0
	s_nop 1
	v_mul_f32_e32 v48, v48, v207
	v_mul_f32_e32 v49, v49, v207
	v_mul_f32_e32 v50, v50, v207
	v_mul_f32_e32 v51, v51, v207
	v_mul_f32_e32 v52, v52, v207
	v_mul_f32_e32 v53, v53, v207
	v_mul_f32_e32 v54, v54, v207
	v_mul_f32_e32 v55, v55, v207
	v_cvt_pk_bf16_f32 v212, v48, v49
	v_cvt_pk_bf16_f32 v213, v50, v51
	v_cvt_pk_bf16_f32 v214, v52, v53
	v_cvt_pk_bf16_f32 v215, v54, v55
	s_nop 1
	global_store_dwordx4 v205, v[212:215], s[50:51] offset:256
	s_nop 1
	v_add_u32_e32 v205, 0xa8000, v204
	v_add_u32_e32 v206, 48, v209
	v_cvt_f32_i32_e32 v206, v206
	v_mul_f32_e32 v206, v208, v206
	v_exp_f32_e32 v207, v206
	s_nop 0
	v_mul_f32_e32 v24, v24, v207
	v_mul_f32_e32 v25, v25, v207
	v_mul_f32_e32 v26, v26, v207
	v_mul_f32_e32 v27, v27, v207
	v_mul_f32_e32 v28, v28, v207
	v_mul_f32_e32 v29, v29, v207
	v_mul_f32_e32 v30, v30, v207
	v_mul_f32_e32 v31, v31, v207
	v_cvt_pk_bf16_f32 v212, v24, v25
	v_cvt_pk_bf16_f32 v213, v26, v27
	v_cvt_pk_bf16_f32 v214, v28, v29
	v_cvt_pk_bf16_f32 v215, v30, v31
	s_nop 1
	global_store_dwordx4 v205, v[212:215], s[50:51] offset:0
	s_nop 1
	v_mul_f32_e32 v56, v56, v207
	v_mul_f32_e32 v57, v57, v207
	v_mul_f32_e32 v58, v58, v207
	v_mul_f32_e32 v59, v59, v207
	v_mul_f32_e32 v60, v60, v207
	v_mul_f32_e32 v61, v61, v207
	v_mul_f32_e32 v62, v62, v207
	v_mul_f32_e32 v63, v63, v207
	v_cvt_pk_bf16_f32 v212, v56, v57
	v_cvt_pk_bf16_f32 v213, v58, v59
	v_cvt_pk_bf16_f32 v214, v60, v61
	v_cvt_pk_bf16_f32 v215, v62, v63
	s_nop 1
	global_store_dwordx4 v205, v[212:215], s[50:51] offset:256
	s_nop 1
	v_add_u32_e32 v205, 0x1c0000, v204
	v_add_u32_e32 v206, 128, v209
	v_cvt_f32_i32_e32 v206, v206
	v_mul_f32_e32 v206, v208, v206
	v_exp_f32_e32 v207, v206
	s_nop 0
	v_mul_f32_e32 v64, v64, v207
	v_mul_f32_e32 v65, v65, v207
	v_mul_f32_e32 v66, v66, v207
	v_mul_f32_e32 v67, v67, v207
	v_mul_f32_e32 v68, v68, v207
	v_mul_f32_e32 v69, v69, v207
	v_mul_f32_e32 v70, v70, v207
	v_mul_f32_e32 v71, v71, v207
	v_cvt_pk_bf16_f32 v212, v64, v65
	v_cvt_pk_bf16_f32 v213, v66, v67
	v_cvt_pk_bf16_f32 v214, v68, v69
	v_cvt_pk_bf16_f32 v215, v70, v71
	s_nop 1
	global_store_dwordx4 v205, v[212:215], s[50:51] offset:0
	s_nop 1
	v_mul_f32_e32 v96, v96, v207
	v_mul_f32_e32 v97, v97, v207
	v_mul_f32_e32 v98, v98, v207
	v_mul_f32_e32 v99, v99, v207
	v_mul_f32_e32 v100, v100, v207
	v_mul_f32_e32 v101, v101, v207
	v_mul_f32_e32 v102, v102, v207
	v_mul_f32_e32 v103, v103, v207
	v_cvt_pk_bf16_f32 v212, v96, v97
	v_cvt_pk_bf16_f32 v213, v98, v99
	v_cvt_pk_bf16_f32 v214, v100, v101
	v_cvt_pk_bf16_f32 v215, v102, v103
	s_nop 1
	global_store_dwordx4 v205, v[212:215], s[50:51] offset:256
	s_nop 1
	v_add_u32_e32 v205, 0x1f8000, v204
	v_add_u32_e32 v206, 144, v209
	v_cvt_f32_i32_e32 v206, v206
	v_mul_f32_e32 v206, v208, v206
	v_exp_f32_e32 v207, v206
	s_nop 0
	v_mul_f32_e32 v72, v72, v207
	v_mul_f32_e32 v73, v73, v207
	v_mul_f32_e32 v74, v74, v207
	v_mul_f32_e32 v75, v75, v207
	v_mul_f32_e32 v76, v76, v207
	v_mul_f32_e32 v77, v77, v207
	v_mul_f32_e32 v78, v78, v207
	v_mul_f32_e32 v79, v79, v207
	v_cvt_pk_bf16_f32 v212, v72, v73
	v_cvt_pk_bf16_f32 v213, v74, v75
	v_cvt_pk_bf16_f32 v214, v76, v77
	v_cvt_pk_bf16_f32 v215, v78, v79
	s_nop 1
	global_store_dwordx4 v205, v[212:215], s[50:51] offset:0
	s_nop 1
	v_mul_f32_e32 v104, v104, v207
	v_mul_f32_e32 v105, v105, v207
	v_mul_f32_e32 v106, v106, v207
	v_mul_f32_e32 v107, v107, v207
	v_mul_f32_e32 v108, v108, v207
	v_mul_f32_e32 v109, v109, v207
	v_mul_f32_e32 v110, v110, v207
	v_mul_f32_e32 v111, v111, v207
	v_cvt_pk_bf16_f32 v212, v104, v105
	v_cvt_pk_bf16_f32 v213, v106, v107
	v_cvt_pk_bf16_f32 v214, v108, v109
	v_cvt_pk_bf16_f32 v215, v110, v111
	s_nop 1
	global_store_dwordx4 v205, v[212:215], s[50:51] offset:256
	s_nop 1
	v_add_u32_e32 v205, 0x230000, v204
	v_add_u32_e32 v206, 160, v209
	v_cvt_f32_i32_e32 v206, v206
	v_mul_f32_e32 v206, v208, v206
	v_exp_f32_e32 v207, v206
	s_nop 0
	v_mul_f32_e32 v80, v80, v207
	v_mul_f32_e32 v81, v81, v207
	v_mul_f32_e32 v82, v82, v207
	v_mul_f32_e32 v83, v83, v207
	v_mul_f32_e32 v84, v84, v207
	v_mul_f32_e32 v85, v85, v207
	v_mul_f32_e32 v86, v86, v207
	v_mul_f32_e32 v87, v87, v207
	v_cvt_pk_bf16_f32 v212, v80, v81
	v_cvt_pk_bf16_f32 v213, v82, v83
	v_cvt_pk_bf16_f32 v214, v84, v85
	v_cvt_pk_bf16_f32 v215, v86, v87
	s_nop 1
	global_store_dwordx4 v205, v[212:215], s[50:51] offset:0
	s_nop 1
	v_mul_f32_e32 v112, v112, v207
	v_mul_f32_e32 v113, v113, v207
	v_mul_f32_e32 v114, v114, v207
	v_mul_f32_e32 v115, v115, v207
	v_mul_f32_e32 v116, v116, v207
	v_mul_f32_e32 v117, v117, v207
	v_mul_f32_e32 v118, v118, v207
	v_mul_f32_e32 v119, v119, v207
	v_cvt_pk_bf16_f32 v212, v112, v113
	v_cvt_pk_bf16_f32 v213, v114, v115
	v_cvt_pk_bf16_f32 v214, v116, v117
	v_cvt_pk_bf16_f32 v215, v118, v119
	s_nop 1
	global_store_dwordx4 v205, v[212:215], s[50:51] offset:256
	s_nop 1
	v_add_u32_e32 v205, 0x268000, v204
	v_add_u32_e32 v206, 176, v209
	v_cvt_f32_i32_e32 v206, v206
	v_mul_f32_e32 v206, v208, v206
	v_exp_f32_e32 v207, v206
	s_nop 0
	v_mul_f32_e32 v88, v88, v207
	v_mul_f32_e32 v89, v89, v207
	v_mul_f32_e32 v90, v90, v207
	v_mul_f32_e32 v91, v91, v207
	v_mul_f32_e32 v92, v92, v207
	v_mul_f32_e32 v93, v93, v207
	v_mul_f32_e32 v94, v94, v207
	v_mul_f32_e32 v95, v95, v207
	v_cvt_pk_bf16_f32 v212, v88, v89
	v_cvt_pk_bf16_f32 v213, v90, v91
	v_cvt_pk_bf16_f32 v214, v92, v93
	v_cvt_pk_bf16_f32 v215, v94, v95
	s_nop 1
	global_store_dwordx4 v205, v[212:215], s[50:51] offset:0
	s_nop 1
	v_mul_f32_e32 v120, v120, v207
	v_mul_f32_e32 v121, v121, v207
	v_mul_f32_e32 v122, v122, v207
	v_mul_f32_e32 v123, v123, v207
	v_mul_f32_e32 v124, v124, v207
	v_mul_f32_e32 v125, v125, v207
	v_mul_f32_e32 v126, v126, v207
	v_mul_f32_e32 v127, v127, v207
	v_cvt_pk_bf16_f32 v212, v120, v121
	v_cvt_pk_bf16_f32 v213, v122, v123
	v_cvt_pk_bf16_f32 v214, v124, v125
	v_cvt_pk_bf16_f32 v215, v126, v127
	s_nop 1
	global_store_dwordx4 v205, v[212:215], s[50:51] offset:256
	s_nop 1
	s_branch .Lp1_ep_done
; __device__ __forceinline__ unsigned cvt_pk_bf16(float lo, float hi) { unsigned r; asm volatile("v_cvt_pk_bf16_f32 %0, %1, %2" : "=v"(r) : "v"(lo), "v"(hi)); return r; }
;     __device__ __forceinline__ void operator()(const f32x4 (&acc)[2][2][4][2], const Unit& u, int wr, int wc, int fr, int fq) const {
;     ...
;         for (int ai = 0; ai < 2; ++ai)
; #pragma unroll
;             for (int m = 0; m < 4; ++m) { const int row = row0 + ai * HALF + m * 16; bf16_t* rowp = O + (size_t)row * ldc + col0;
;                 float sc = 1.f;
;                 if (mode) { const float e = (float)((row & 2047) - 1024) * lg; sc = (mode == 1) ? __builtin_amdgcn_exp2f(e) : __builtin_amdgcn_exp2f(-e) * 0.0625f; }
; #pragma unroll
;                 for (int bj = 0; bj < 2; ++bj) { const f32x4 v0 = acc[ai][bj][m][0] * sc, v1 = acc[ai][bj][m][1] * sc;
;                     u32x4 w; w.x = cvt_pk_bf16(v0[0], v0[1]); w.y = cvt_pk_bf16(v0[2], v0[3]); w.z = cvt_pk_bf16(v1[0], v1[1]); w.w = cvt_pk_bf16(v1[2], v1[3]);
;                     *(u32x4*)(rowp + bj * HALF) = w; } }
.Lp1_ep_mode2:
	v_add_u32_e32 v205, 0x0, v204
	v_add_u32_e32 v206, 0, v209
	v_cvt_f32_i32_e32 v206, v206
	v_mul_f32_e32 v206, v208, v206
	v_exp_f32_e64 v207, -v206
	s_nop 0
	v_mul_f32_e32 v207, 0x3d800000, v207
	v_mul_f32_e32 v0, v0, v207
	v_mul_f32_e32 v1, v1, v207
	v_mul_f32_e32 v2, v2, v207
	v_mul_f32_e32 v3, v3, v207
	v_mul_f32_e32 v4, v4, v207
	v_mul_f32_e32 v5, v5, v207
	v_mul_f32_e32 v6, v6, v207
	v_mul_f32_e32 v7, v7, v207
	v_cvt_pk_bf16_f32 v212, v0, v1
	v_cvt_pk_bf16_f32 v213, v2, v3
	v_cvt_pk_bf16_f32 v214, v4, v5
	v_cvt_pk_bf16_f32 v215, v6, v7
	s_nop 1
	global_store_dwordx4 v205, v[212:215], s[50:51] offset:0
	s_nop 1
	v_mul_f32_e32 v32, v32, v207
	v_mul_f32_e32 v33, v33, v207
	v_mul_f32_e32 v34, v34, v207
	v_mul_f32_e32 v35, v35, v207
	v_mul_f32_e32 v36, v36, v207
	v_mul_f32_e32 v37, v37, v207
	v_mul_f32_e32 v38, v38, v207
	v_mul_f32_e32 v39, v39, v207
	v_cvt_pk_bf16_f32 v212, v32, v33
	v_cvt_pk_bf16_f32 v213, v34, v35
	v_cvt_pk_bf16_f32 v214, v36, v37
	v_cvt_pk_bf16_f32 v215, v38, v39
	s_nop 1
	global_store_dwordx4 v205, v[212:215], s[50:51] offset:256
	s_nop 1
	v_add_u32_e32 v205, 0x38000, v204
	v_add_u32_e32 v206, 16, v209
	v_cvt_f32_i32_e32 v206, v206
	v_mul_f32_e32 v206, v208, v206
	v_exp_f32_e64 v207, -v206
	s_nop 0
	v_mul_f32_e32 v207, 0x3d800000, v207
	v_mul_f32_e32 v8, v8, v207
	v_mul_f32_e32 v9, v9, v207
	v_mul_f32_e32 v10, v10, v207
	v_mul_f32_e32 v11, v11, v207
	v_mul_f32_e32 v12, v12, v207
	v_mul_f32_e32 v13, v13, v207
	v_mul_f32_e32 v14, v14, v207
	v_mul_f32_e32 v15, v15, v207
	v_cvt_pk_bf16_f32 v212, v8, v9
	v_cvt_pk_bf16_f32 v213, v10, v11
	v_cvt_pk_bf16_f32 v214, v12, v13
	v_cvt_pk_bf16_f32 v215, v14, v15
	s_nop 1
	global_store_dwordx4 v205, v[212:215], s[50:51] offset:0
	s_nop 1
	v_mul_f32_e32 v40, v40, v207
	v_mul_f32_e32 v41, v41, v207
	v_mul_f32_e32 v42, v42, v207
	v_mul_f32_e32 v43, v43, v207
	v_mul_f32_e32 v44, v44, v207
	v_mul_f32_e32 v45, v45, v207
	v_mul_f32_e32 v46, v46, v207
	v_mul_f32_e32 v47, v47, v207
	v_cvt_pk_bf16_f32 v212, v40, v41
	v_cvt_pk_bf16_f32 v213, v42, v43
	v_cvt_pk_bf16_f32 v214, v44, v45
	v_cvt_pk_bf16_f32 v215, v46, v47
	s_nop 1
	global_store_dwordx4 v205, v[212:215], s[50:51] offset:256
	s_nop 1
	v_add_u32_e32 v205, 0x70000, v204
	v_add_u32_e32 v206, 32, v209
	v_cvt_f32_i32_e32 v206, v206
	v_mul_f32_e32 v206, v208, v206
	v_exp_f32_e64 v207, -v206
	s_nop 0
	v_mul_f32_e32 v207, 0x3d800000, v207
	v_mul_f32_e32 v16, v16, v207
	v_mul_f32_e32 v17, v17, v207
	v_mul_f32_e32 v18, v18, v207
	v_mul_f32_e32 v19, v19, v207
	v_mul_f32_e32 v20, v20, v207
	v_mul_f32_e32 v21, v21, v207
	v_mul_f32_e32 v22, v22, v207
	v_mul_f32_e32 v23, v23, v207
	v_cvt_pk_bf16_f32 v212, v16, v17
	v_cvt_pk_bf16_f32 v213, v18, v19
	v_cvt_pk_bf16_f32 v214, v20, v21
	v_cvt_pk_bf16_f32 v215, v22, v23
	s_nop 1
	global_store_dwordx4 v205, v[212:215], s[50:51] offset:0
	s_nop 1
	v_mul_f32_e32 v48, v48, v207
	v_mul_f32_e32 v49, v49, v207
	v_mul_f32_e32 v50, v50, v207
	v_mul_f32_e32 v51, v51, v207
	v_mul_f32_e32 v52, v52, v207
	v_mul_f32_e32 v53, v53, v207
	v_mul_f32_e32 v54, v54, v207
	v_mul_f32_e32 v55, v55, v207
	v_cvt_pk_bf16_f32 v212, v48, v49
	v_cvt_pk_bf16_f32 v213, v50, v51
	v_cvt_pk_bf16_f32 v214, v52, v53
	v_cvt_pk_bf16_f32 v215, v54, v55
	s_nop 1
	global_store_dwordx4 v205, v[212:215], s[50:51] offset:256
	s_nop 1
	v_add_u32_e32 v205, 0xa8000, v204
	v_add_u32_e32 v206, 48, v209
	v_cvt_f32_i32_e32 v206, v206
	v_mul_f32_e32 v206, v208, v206
	v_exp_f32_e64 v207, -v206
	s_nop 0
	v_mul_f32_e32 v207, 0x3d800000, v207
	v_mul_f32_e32 v24, v24, v207
	v_mul_f32_e32 v25, v25, v207
	v_mul_f32_e32 v26, v26, v207
	v_mul_f32_e32 v27, v27, v207
	v_mul_f32_e32 v28, v28, v207
	v_mul_f32_e32 v29, v29, v207
	v_mul_f32_e32 v30, v30, v207
	v_mul_f32_e32 v31, v31, v207
	v_cvt_pk_bf16_f32 v212, v24, v25
	v_cvt_pk_bf16_f32 v213, v26, v27
	v_cvt_pk_bf16_f32 v214, v28, v29
	v_cvt_pk_bf16_f32 v215, v30, v31
	s_nop 1
	global_store_dwordx4 v205, v[212:215], s[50:51] offset:0
	s_nop 1
	v_mul_f32_e32 v56, v56, v207
	v_mul_f32_e32 v57, v57, v207
	v_mul_f32_e32 v58, v58, v207
	v_mul_f32_e32 v59, v59, v207
	v_mul_f32_e32 v60, v60, v207
	v_mul_f32_e32 v61, v61, v207
	v_mul_f32_e32 v62, v62, v207
	v_mul_f32_e32 v63, v63, v207
	v_cvt_pk_bf16_f32 v212, v56, v57
	v_cvt_pk_bf16_f32 v213, v58, v59
	v_cvt_pk_bf16_f32 v214, v60, v61
	v_cvt_pk_bf16_f32 v215, v62, v63
	s_nop 1
	global_store_dwordx4 v205, v[212:215], s[50:51] offset:256
	s_nop 1
	v_add_u32_e32 v205, 0x1c0000, v204
	v_add_u32_e32 v206, 128, v209
	v_cvt_f32_i32_e32 v206, v206
	v_mul_f32_e32 v206, v208, v206
	v_exp_f32_e64 v207, -v206
	s_nop 0
	v_mul_f32_e32 v207, 0x3d800000, v207
	v_mul_f32_e32 v64, v64, v207
	v_mul_f32_e32 v65, v65, v207
	v_mul_f32_e32 v66, v66, v207
	v_mul_f32_e32 v67, v67, v207
	v_mul_f32_e32 v68, v68, v207
	v_mul_f32_e32 v69, v69, v207
	v_mul_f32_e32 v70, v70, v207
	v_mul_f32_e32 v71, v71, v207
	v_cvt_pk_bf16_f32 v212, v64, v65
	v_cvt_pk_bf16_f32 v213, v66, v67
	v_cvt_pk_bf16_f32 v214, v68, v69
	v_cvt_pk_bf16_f32 v215, v70, v71
	s_nop 1
	global_store_dwordx4 v205, v[212:215], s[50:51] offset:0
	s_nop 1
	v_mul_f32_e32 v96, v96, v207
	v_mul_f32_e32 v97, v97, v207
	v_mul_f32_e32 v98, v98, v207
	v_mul_f32_e32 v99, v99, v207
	v_mul_f32_e32 v100, v100, v207
	v_mul_f32_e32 v101, v101, v207
	v_mul_f32_e32 v102, v102, v207
	v_mul_f32_e32 v103, v103, v207
	v_cvt_pk_bf16_f32 v212, v96, v97
	v_cvt_pk_bf16_f32 v213, v98, v99
	v_cvt_pk_bf16_f32 v214, v100, v101
	v_cvt_pk_bf16_f32 v215, v102, v103
	s_nop 1
	global_store_dwordx4 v205, v[212:215], s[50:51] offset:256
	s_nop 1
	v_add_u32_e32 v205, 0x1f8000, v204
	v_add_u32_e32 v206, 144, v209
	v_cvt_f32_i32_e32 v206, v206
; __device__ __forceinline__ unsigned cvt_pk_bf16(float lo, float hi) { unsigned r; asm volatile("v_cvt_pk_bf16_f32 %0, %1, %2" : "=v"(r) : "v"(lo), "v"(hi)); return r; }
;     __device__ __forceinline__ void operator()(const f32x4 (&acc)[2][2][4][2], const Unit& u, int wr, int wc, int fr, int fq) const {
;     ...
;         for (int ai = 0; ai < 2; ++ai)
; #pragma unroll
;             for (int m = 0; m < 4; ++m) { const int row = row0 + ai * HALF + m * 16; bf16_t* rowp = O + (size_t)row * ldc + col0;
;                 float sc = 1.f;
;                 if (mode) { const float e = (float)((row & 2047) - 1024) * lg; sc = (mode == 1) ? __builtin_amdgcn_exp2f(e) : __builtin_amdgcn_exp2f(-e) * 0.0625f; }
; #pragma unroll
;                 for (int bj = 0; bj < 2; ++bj) { const f32x4 v0 = acc[ai][bj][m][0] * sc, v1 = acc[ai][bj][m][1] * sc;
;                     u32x4 w; w.x = cvt_pk_bf16(v0[0], v0[1]); w.y = cvt_pk_bf16(v0[2], v0[3]); w.z = cvt_pk_bf16(v1[0], v1[1]); w.w = cvt_pk_bf16(v1[2], v1[3]);
;                     *(u32x4*)(rowp + bj * HALF) = w; } }
	v_mul_f32_e32 v206, v208, v206
	v_exp_f32_e64 v207, -v206
	s_nop 0
	v_mul_f32_e32 v207, 0x3d800000, v207
	v_mul_f32_e32 v72, v72, v207
	v_mul_f32_e32 v73, v73, v207
	v_mul_f32_e32 v74, v74, v207
	v_mul_f32_e32 v75, v75, v207
	v_mul_f32_e32 v76, v76, v207
	v_mul_f32_e32 v77, v77, v207
	v_mul_f32_e32 v78, v78, v207
	v_mul_f32_e32 v79, v79, v207
	v_cvt_pk_bf16_f32 v212, v72, v73
	v_cvt_pk_bf16_f32 v213, v74, v75
	v_cvt_pk_bf16_f32 v214, v76, v77
	v_cvt_pk_bf16_f32 v215, v78, v79
	s_nop 1
	global_store_dwordx4 v205, v[212:215], s[50:51] offset:0
	s_nop 1
	v_mul_f32_e32 v104, v104, v207
	v_mul_f32_e32 v105, v105, v207
	v_mul_f32_e32 v106, v106, v207
	v_mul_f32_e32 v107, v107, v207
	v_mul_f32_e32 v108, v108, v207
	v_mul_f32_e32 v109, v109, v207
	v_mul_f32_e32 v110, v110, v207
	v_mul_f32_e32 v111, v111, v207
	v_cvt_pk_bf16_f32 v212, v104, v105
	v_cvt_pk_bf16_f32 v213, v106, v107
	v_cvt_pk_bf16_f32 v214, v108, v109
	v_cvt_pk_bf16_f32 v215, v110, v111
	s_nop 1
	global_store_dwordx4 v205, v[212:215], s[50:51] offset:256
	s_nop 1
	v_add_u32_e32 v205, 0x230000, v204
	v_add_u32_e32 v206, 160, v209
	v_cvt_f32_i32_e32 v206, v206
	v_mul_f32_e32 v206, v208, v206
	v_exp_f32_e64 v207, -v206
	s_nop 0
	v_mul_f32_e32 v207, 0x3d800000, v207
	v_mul_f32_e32 v80, v80, v207
	v_mul_f32_e32 v81, v81, v207
	v_mul_f32_e32 v82, v82, v207
	v_mul_f32_e32 v83, v83, v207
	v_mul_f32_e32 v84, v84, v207
	v_mul_f32_e32 v85, v85, v207
	v_mul_f32_e32 v86, v86, v207
	v_mul_f32_e32 v87, v87, v207
	v_cvt_pk_bf16_f32 v212, v80, v81
	v_cvt_pk_bf16_f32 v213, v82, v83
	v_cvt_pk_bf16_f32 v214, v84, v85
	v_cvt_pk_bf16_f32 v215, v86, v87
	s_nop 1
	global_store_dwordx4 v205, v[212:215], s[50:51] offset:0
	s_nop 1
	v_mul_f32_e32 v112, v112, v207
	v_mul_f32_e32 v113, v113, v207
	v_mul_f32_e32 v114, v114, v207
	v_mul_f32_e32 v115, v115, v207
	v_mul_f32_e32 v116, v116, v207
	v_mul_f32_e32 v117, v117, v207
	v_mul_f32_e32 v118, v118, v207
	v_mul_f32_e32 v119, v119, v207
	v_cvt_pk_bf16_f32 v212, v112, v113
	v_cvt_pk_bf16_f32 v213, v114, v115
	v_cvt_pk_bf16_f32 v214, v116, v117
	v_cvt_pk_bf16_f32 v215, v118, v119
	s_nop 1
	global_store_dwordx4 v205, v[212:215], s[50:51] offset:256
	s_nop 1
	v_add_u32_e32 v205, 0x268000, v204
	v_add_u32_e32 v206, 176, v209
	v_cvt_f32_i32_e32 v206, v206
	v_mul_f32_e32 v206, v208, v206
	v_exp_f32_e64 v207, -v206
	s_nop 0
	v_mul_f32_e32 v207, 0x3d800000, v207
	v_mul_f32_e32 v88, v88, v207
	v_mul_f32_e32 v89, v89, v207
	v_mul_f32_e32 v90, v90, v207
	v_mul_f32_e32 v91, v91, v207
	v_mul_f32_e32 v92, v92, v207
	v_mul_f32_e32 v93, v93, v207
	v_mul_f32_e32 v94, v94, v207
	v_mul_f32_e32 v95, v95, v207
	v_cvt_pk_bf16_f32 v212, v88, v89
	v_cvt_pk_bf16_f32 v213, v90, v91
	v_cvt_pk_bf16_f32 v214, v92, v93
	v_cvt_pk_bf16_f32 v215, v94, v95
	s_nop 1
	global_store_dwordx4 v205, v[212:215], s[50:51] offset:0
	s_nop 1
	v_mul_f32_e32 v120, v120, v207
	v_mul_f32_e32 v121, v121, v207
	v_mul_f32_e32 v122, v122, v207
	v_mul_f32_e32 v123, v123, v207
	v_mul_f32_e32 v124, v124, v207
	v_mul_f32_e32 v125, v125, v207
	v_mul_f32_e32 v126, v126, v207
	v_mul_f32_e32 v127, v127, v207
	v_cvt_pk_bf16_f32 v212, v120, v121
	v_cvt_pk_bf16_f32 v213, v122, v123
	v_cvt_pk_bf16_f32 v214, v124, v125
	v_cvt_pk_bf16_f32 v215, v126, v127
	s_nop 1
	global_store_dwordx4 v205, v[212:215], s[50:51] offset:256
	s_nop 1
	s_branch .Lp1_ep_done
.Lp1_ep_plain:
	v_add_u32_e32 v205, 0x0, v204
	v_cvt_pk_bf16_f32 v212, v0, v1
	v_cvt_pk_bf16_f32 v213, v2, v3
	v_cvt_pk_bf16_f32 v214, v4, v5
	v_cvt_pk_bf16_f32 v215, v6, v7
	s_nop 1
	global_store_dwordx4 v205, v[212:215], s[50:51] offset:0
	s_nop 1
	v_cvt_pk_bf16_f32 v212, v32, v33
	v_cvt_pk_bf16_f32 v213, v34, v35
	v_cvt_pk_bf16_f32 v214, v36, v37
	v_cvt_pk_bf16_f32 v215, v38, v39
	s_nop 1
	global_store_dwordx4 v205, v[212:215], s[50:51] offset:256
	s_nop 1
	v_add_u32_e32 v205, 0x38000, v204
	v_cvt_pk_bf16_f32 v212, v8, v9
	v_cvt_pk_bf16_f32 v213, v10, v11
	v_cvt_pk_bf16_f32 v214, v12, v13
	v_cvt_pk_bf16_f32 v215, v14, v15
	s_nop 1
	global_store_dwordx4 v205, v[212:215], s[50:51] offset:0
	s_nop 1
	v_cvt_pk_bf16_f32 v212, v40, v41
	v_cvt_pk_bf16_f32 v213, v42, v43
	v_cvt_pk_bf16_f32 v214, v44, v45
	v_cvt_pk_bf16_f32 v215, v46, v47
	s_nop 1
	global_store_dwordx4 v205, v[212:215], s[50:51] offset:256
	s_nop 1
	v_add_u32_e32 v205, 0x70000, v204
	v_cvt_pk_bf16_f32 v212, v16, v17
	v_cvt_pk_bf16_f32 v213, v18, v19
	v_cvt_pk_bf16_f32 v214, v20, v21
	v_cvt_pk_bf16_f32 v215, v22, v23
	s_nop 1
	global_store_dwordx4 v205, v[212:215], s[50:51] offset:0
	s_nop 1
	v_cvt_pk_bf16_f32 v212, v48, v49
	v_cvt_pk_bf16_f32 v213, v50, v51
	v_cvt_pk_bf16_f32 v214, v52, v53
	v_cvt_pk_bf16_f32 v215, v54, v55
	s_nop 1
	global_store_dwordx4 v205, v[212:215], s[50:51] offset:256
	s_nop 1
	v_add_u32_e32 v205, 0xa8000, v204
	v_cvt_pk_bf16_f32 v212, v24, v25
	v_cvt_pk_bf16_f32 v213, v26, v27
	v_cvt_pk_bf16_f32 v214, v28, v29
	v_cvt_pk_bf16_f32 v215, v30, v31
	s_nop 1
	global_store_dwordx4 v205, v[212:215], s[50:51] offset:0
	s_nop 1
	v_cvt_pk_bf16_f32 v212, v56, v57
	v_cvt_pk_bf16_f32 v213, v58, v59
	v_cvt_pk_bf16_f32 v214, v60, v61
	v_cvt_pk_bf16_f32 v215, v62, v63
	s_nop 1
	global_store_dwordx4 v205, v[212:215], s[50:51] offset:256
	s_nop 1
	v_add_u32_e32 v205, 0x1c0000, v204
	v_cvt_pk_bf16_f32 v212, v64, v65
	v_cvt_pk_bf16_f32 v213, v66, v67
	v_cvt_pk_bf16_f32 v214, v68, v69
	v_cvt_pk_bf16_f32 v215, v70, v71
	s_nop 1
	global_store_dwordx4 v205, v[212:215], s[50:51] offset:0
	s_nop 1
	v_cvt_pk_bf16_f32 v212, v96, v97
	v_cvt_pk_bf16_f32 v213, v98, v99
	v_cvt_pk_bf16_f32 v214, v100, v101
	v_cvt_pk_bf16_f32 v215, v102, v103
	s_nop 1
	global_store_dwordx4 v205, v[212:215], s[50:51] offset:256
	s_nop 1
	v_add_u32_e32 v205, 0x1f8000, v204
	v_cvt_pk_bf16_f32 v212, v72, v73
	v_cvt_pk_bf16_f32 v213, v74, v75
	v_cvt_pk_bf16_f32 v214, v76, v77
	v_cvt_pk_bf16_f32 v215, v78, v79
	s_nop 1
	global_store_dwordx4 v205, v[212:215], s[50:51] offset:0
	s_nop 1
	v_cvt_pk_bf16_f32 v212, v104, v105
	v_cvt_pk_bf16_f32 v213, v106, v107
	v_cvt_pk_bf16_f32 v214, v108, v109
	v_cvt_pk_bf16_f32 v215, v110, v111
	s_nop 1
	global_store_dwordx4 v205, v[212:215], s[50:51] offset:256
	s_nop 1
	v_add_u32_e32 v205, 0x230000, v204
	v_cvt_pk_bf16_f32 v212, v80, v81
	v_cvt_pk_bf16_f32 v213, v82, v83
	v_cvt_pk_bf16_f32 v214, v84, v85
	v_cvt_pk_bf16_f32 v215, v86, v87
	s_nop 1
	global_store_dwordx4 v205, v[212:215], s[50:51] offset:0
	s_nop 1
	v_cvt_pk_bf16_f32 v212, v112, v113
	v_cvt_pk_bf16_f32 v213, v114, v115
	v_cvt_pk_bf16_f32 v214, v116, v117
	v_cvt_pk_bf16_f32 v215, v118, v119
	s_nop 1
	global_store_dwordx4 v205, v[212:215], s[50:51] offset:256
	s_nop 1
	v_add_u32_e32 v205, 0x268000, v204
	v_cvt_pk_bf16_f32 v212, v88, v89
	v_cvt_pk_bf16_f32 v213, v90, v91
	v_cvt_pk_bf16_f32 v214, v92, v93
	v_cvt_pk_bf16_f32 v215, v94, v95
	s_nop 1
	global_store_dwordx4 v205, v[212:215], s[50:51] offset:0
	s_nop 1
	v_cvt_pk_bf16_f32 v212, v120, v121
	v_cvt_pk_bf16_f32 v213, v122, v123
	v_cvt_pk_bf16_f32 v214, v124, v125
	v_cvt_pk_bf16_f32 v215, v126, v127
	s_nop 1
	global_store_dwordx4 v205, v[212:215], s[50:51] offset:256
	s_nop 1
; __device__ __forceinline__ unsigned cvtpk2(float lo, float hi) { unsigned r; asm volatile("v_cvt_pk_bf16_f32 %0, %1, %2" : "=v"(r) : "v"(lo), "v"(hi)); return r; }
; template <class Epi, class Sched, bool ALIGN_EPI = false, bool SP2 = false>
; __device__ __forceinline__ void gemm_phase(PG8_LAS unsigned char* lds, const Gemm g, const Sched& S, const Epi& E) {
;     ...
;         if constexpr (!Epi::AFTER_DRAIN) { E(acc, cur, wr, wc, fr, fq); S.done(cur); }
;         if (!has_next) break;
; #pragma unroll
;         for (int a = 0; a < 2; ++a)
; #pragma unroll
;             for (int b = 0; b < 2; ++b)
; #pragma unroll
;                 for (int m = 0; m < 4; ++m)
; #pragma unroll
;                     for (int n = 0; n < 2; ++n) acc[a][b][m][n] = (f32x4){0.f, 0.f, 0.f, 0.f};
;         cur = nxt; cA = nA; cB = nB; ++ui;
; __device__ __forceinline__ void p0_transpose_item(const float* __restrict__ W, int K, int N, bf16* __restrict__ WT, int mode, const float* __restrict__ kscale, int item, int lane) {
;     ...
;     if (kscale) {
; #pragma unroll
;         for (int i = 0; i < 64; ++i) v[i] *= kscale[k0 + i]; }
;     const int rbase = (mode == 0) ? n0 : (256 * (n0 >> 7) + (n0 & 127) + (mode == 2 ? 128 : 0));
;     bf16* dst = WT + (size_t)(rbase + lane) * K + k0;
; #pragma unroll
;     for (int j = 0; j < 8; ++j) { v4u o; o.x = cvtpk2(v[8 * j], v[8 * j + 1]); o.y = cvtpk2(v[8 * j + 2], v[8 * j + 3]); o.z = cvtpk2(v[8 * j + 4], v[8 * j + 5]); o.w = cvtpk2(v[8 * j + 6], v[8 * j + 7]);
;         *(v4u*)(dst + 8 * j) = o; }
.Lp1_ep_done:
	s_cmp_eq_u32 s39, 0
	s_cbranch_scc1 .Lp1_cf_skip_u
	s_waitcnt vmcnt(16)
	s_cmp_eq_u32 s9, 0
	s_cbranch_scc1 .Lp1_cf_nosc_u
	v_readlane_b32 s40, v197, 0
	v_readlane_b32 s41, v197, 1
	v_readlane_b32 s42, v197, 2
	v_readlane_b32 s43, v197, 3
	v_mul_f32_e32 v128, s40, v128
	v_readlane_b32 s40, v197, 4
	v_mul_f32_e32 v129, s41, v129
	v_readlane_b32 s41, v197, 5
	v_mul_f32_e32 v130, s42, v130
	v_readlane_b32 s42, v197, 6
	v_mul_f32_e32 v131, s43, v131
	v_readlane_b32 s43, v197, 7
	v_mul_f32_e32 v132, s40, v132
	v_readlane_b32 s40, v197, 8
	v_mul_f32_e32 v133, s41, v133
	v_readlane_b32 s41, v197, 9
	v_mul_f32_e32 v134, s42, v134
	v_readlane_b32 s42, v197, 10
	v_mul_f32_e32 v135, s43, v135
	v_readlane_b32 s43, v197, 11
	v_mul_f32_e32 v136, s40, v136
	v_readlane_b32 s40, v197, 12
	v_mul_f32_e32 v137, s41, v137
	v_readlane_b32 s41, v197, 13
	v_mul_f32_e32 v138, s42, v138
	v_readlane_b32 s42, v197, 14
	v_mul_f32_e32 v139, s43, v139
	v_readlane_b32 s43, v197, 15
	v_mul_f32_e32 v140, s40, v140
	v_readlane_b32 s40, v197, 16
	v_mul_f32_e32 v141, s41, v141
	v_readlane_b32 s41, v197, 17
	v_mul_f32_e32 v142, s42, v142
	v_readlane_b32 s42, v197, 18
	v_mul_f32_e32 v143, s43, v143
	v_readlane_b32 s43, v197, 19
	v_mul_f32_e32 v144, s40, v144
	v_readlane_b32 s40, v197, 20
	v_mul_f32_e32 v145, s41, v145
	v_readlane_b32 s41, v197, 21
	v_mul_f32_e32 v146, s42, v146
	v_readlane_b32 s42, v197, 22
	v_mul_f32_e32 v147, s43, v147
	v_readlane_b32 s43, v197, 23
	v_mul_f32_e32 v148, s40, v148
	v_readlane_b32 s40, v197, 24
	v_mul_f32_e32 v149, s41, v149
	v_readlane_b32 s41, v197, 25
	v_mul_f32_e32 v150, s42, v150
	v_readlane_b32 s42, v197, 26
	v_mul_f32_e32 v151, s43, v151
	v_readlane_b32 s43, v197, 27
	v_mul_f32_e32 v152, s40, v152
	v_readlane_b32 s40, v197, 28
	v_mul_f32_e32 v153, s41, v153
	v_readlane_b32 s41, v197, 29
	v_mul_f32_e32 v154, s42, v154
	v_readlane_b32 s42, v197, 30
	v_mul_f32_e32 v155, s43, v155
	v_readlane_b32 s43, v197, 31
	v_mul_f32_e32 v156, s40, v156
	v_readlane_b32 s40, v197, 32
	v_mul_f32_e32 v157, s41, v157
	v_readlane_b32 s41, v197, 33
	v_mul_f32_e32 v158, s42, v158
	v_readlane_b32 s42, v197, 34
	v_mul_f32_e32 v159, s43, v159
	v_readlane_b32 s43, v197, 35
	v_mul_f32_e32 v160, s40, v160
	v_readlane_b32 s40, v197, 36
	v_mul_f32_e32 v161, s41, v161
	v_readlane_b32 s41, v197, 37
	v_mul_f32_e32 v162, s42, v162
	v_readlane_b32 s42, v197, 38
	v_mul_f32_e32 v163, s43, v163
	v_readlane_b32 s43, v197, 39
	v_mul_f32_e32 v164, s40, v164
	v_readlane_b32 s40, v197, 40
	v_mul_f32_e32 v165, s41, v165
	v_readlane_b32 s41, v197, 41
	v_mul_f32_e32 v166, s42, v166
	v_readlane_b32 s42, v197, 42
	v_mul_f32_e32 v167, s43, v167
	v_readlane_b32 s43, v197, 43
	v_mul_f32_e32 v168, s40, v168
	v_readlane_b32 s40, v197, 44
	v_mul_f32_e32 v169, s41, v169
	v_readlane_b32 s41, v197, 45
	v_mul_f32_e32 v170, s42, v170
	v_readlane_b32 s42, v197, 46
	v_mul_f32_e32 v171, s43, v171
	v_readlane_b32 s43, v197, 47
	v_mul_f32_e32 v172, s40, v172
	v_readlane_b32 s40, v197, 48
	v_mul_f32_e32 v173, s41, v173
	v_readlane_b32 s41, v197, 49
	v_mul_f32_e32 v174, s42, v174
	v_readlane_b32 s42, v197, 50
	v_mul_f32_e32 v175, s43, v175
	v_readlane_b32 s43, v197, 51
	v_mul_f32_e32 v176, s40, v176
	v_readlane_b32 s40, v197, 52
	v_mul_f32_e32 v177, s41, v177
	v_readlane_b32 s41, v197, 53
	v_mul_f32_e32 v178, s42, v178
	v_readlane_b32 s42, v197, 54
	v_mul_f32_e32 v179, s43, v179
	v_readlane_b32 s43, v197, 55
	v_mul_f32_e32 v180, s40, v180
	v_readlane_b32 s40, v197, 56
	v_mul_f32_e32 v181, s41, v181
	v_readlane_b32 s41, v197, 57
	v_mul_f32_e32 v182, s42, v182
	v_readlane_b32 s42, v197, 58
	v_mul_f32_e32 v183, s43, v183
	v_readlane_b32 s43, v197, 59
	v_mul_f32_e32 v188, s40, v188
	v_readlane_b32 s40, v197, 60
	v_mul_f32_e32 v189, s41, v189
	v_readlane_b32 s41, v197, 61
	v_mul_f32_e32 v190, s42, v190
	v_readlane_b32 s42, v197, 62
	v_mul_f32_e32 v191, s43, v191
	v_readlane_b32 s43, v197, 63
	v_mul_f32_e32 v192, s40, v192
	s_nop 0
	v_mul_f32_e32 v193, s41, v193
	s_nop 0
	v_mul_f32_e32 v194, s42, v194
	s_nop 0
	v_mul_f32_e32 v195, s43, v195
.Lp1_cf_nosc_u:
	v_cvt_pk_bf16_f32 v200, v128, v129
	v_cvt_pk_bf16_f32 v201, v130, v131
	v_cvt_pk_bf16_f32 v202, v132, v133
	v_cvt_pk_bf16_f32 v203, v134, v135
	global_store_dwordx4 v198, v[200:203], s[52:53] offset:0
	s_nop 1
	v_cvt_pk_bf16_f32 v200, v136, v137
	v_cvt_pk_bf16_f32 v201, v138, v139
	v_cvt_pk_bf16_f32 v202, v140, v141
	v_cvt_pk_bf16_f32 v203, v142, v143
	global_store_dwordx4 v198, v[200:203], s[52:53] offset:16
	s_nop 1
	v_cvt_pk_bf16_f32 v200, v144, v145
	v_cvt_pk_bf16_f32 v201, v146, v147
	v_cvt_pk_bf16_f32 v202, v148, v149
	v_cvt_pk_bf16_f32 v203, v150, v151
	global_store_dwordx4 v198, v[200:203], s[52:53] offset:32
	s_nop 1
	v_cvt_pk_bf16_f32 v200, v152, v153
	v_cvt_pk_bf16_f32 v201, v154, v155
	v_cvt_pk_bf16_f32 v202, v156, v157
	v_cvt_pk_bf16_f32 v203, v158, v159
	global_store_dwordx4 v198, v[200:203], s[52:53] offset:48
	s_nop 1
	v_cvt_pk_bf16_f32 v200, v160, v161
	v_cvt_pk_bf16_f32 v201, v162, v163
	v_cvt_pk_bf16_f32 v202, v164, v165
	v_cvt_pk_bf16_f32 v203, v166, v167
	global_store_dwordx4 v198, v[200:203], s[52:53] offset:64
	s_nop 1
	v_cvt_pk_bf16_f32 v200, v168, v169
	v_cvt_pk_bf16_f32 v201, v170, v171
	v_cvt_pk_bf16_f32 v202, v172, v173
	v_cvt_pk_bf16_f32 v203, v174, v175
	global_store_dwordx4 v198, v[200:203], s[52:53] offset:80
	s_nop 1
	v_cvt_pk_bf16_f32 v200, v176, v177
	v_cvt_pk_bf16_f32 v201, v178, v179
	v_cvt_pk_bf16_f32 v202, v180, v181
	v_cvt_pk_bf16_f32 v203, v182, v183
	global_store_dwordx4 v198, v[200:203], s[52:53] offset:96
	s_nop 1
	v_cvt_pk_bf16_f32 v200, v188, v189
	v_cvt_pk_bf16_f32 v201, v190, v191
	v_cvt_pk_bf16_f32 v202, v192, v193
	v_cvt_pk_bf16_f32 v203, v194, v195
	global_store_dwordx4 v198, v[200:203], s[52:53] offset:112
	s_nop 1
	s_add_u32 s6, s6, s7
.Lp1_cf_skip_u:
	s_cmp_eq_u32 s19, 0
	s_cbranch_scc1 .Lp1_done
	s_mov_b32 s17, s20
	s_mov_b32 s18, s21
	s_mov_b64 s[22:23], s[26:27]
	s_mov_b64 s[24:25], s[28:29]
	s_add_u32 s16, s16, 1
	s_branch .Lp1_unit

;     __device__ __forceinline__ void convert(int r, int lane) const {
;         if (r < I_OUT) { p0_transpose_item(w_out, DM, DM, Wout_t, 0, nullptr, r, lane); return; } r -= I_OUT;
;         if (r < I_G) { p0_transpose_item(w_gate, DM, FF, Wgu_t, 1, kscale, r, lane); return; } r -= I_G;
;         if (r < I_G) { p0_transpose_item(w_up, DM, FF, Wgu_t, 2, kscale, r, lane); return; } r -= I_G;
;         p0_transpose_item(w_down, FF, DM, Wdn_t, 0, nullptr, r, lane);
;     }
;     __device__ __forceinline__ void done(const pg8::Unit&) const {
;         if (nxt < NITEMS) { convert(nxt, (int)(threadIdx.x & 63)); nxt += ngw; }
;     }
;     __device__ __forceinline__ void finish() const { while (nxt < NITEMS) { convert(nxt, (int)(threadIdx.x & 63)); nxt += ngw; } }
.Lp1_exit:
.Lp1_fin_loop:
	s_cmp_lt_u32 s6, 9472
	s_cbranch_scc0 .Lp1_fin_done
	s_cmp_lt_u32 s6, 9472
	s_cselect_b32 s39, 1, 0
	s_cbranch_scc0 .Lp1_cv_skip_f
	s_mov_b32 s40, s6
	s_cmp_lt_u32 s40, 1024
	s_cbranch_scc1 .Lp1_cv_out_f
	s_sub_u32 s40, s40, 1024
	s_cmp_lt_u32 s40, 2816
	s_cbranch_scc1 .Lp1_cv_gate_f
	s_sub_u32 s40, s40, 2816
	s_cmp_lt_u32 s40, 2816
	s_cbranch_scc1 .Lp1_cv_up_f
	s_sub_u32 s40, s40, 2816
	v_readlane_b32 s48, v244, 26
	v_readlane_b32 s49, v244, 27
	s_movk_i32 s41, 2048
	s_movk_i32 s42, 5632
	s_mov_b32 s43, 0x5100000
	s_mov_b32 s9, 0
	s_branch .Lp1_cv_dec_f

; __device__ __forceinline__ unsigned cvtpk2(float lo, float hi) { unsigned r; asm volatile("v_cvt_pk_bf16_f32 %0, %1, %2" : "=v"(r) : "v"(lo), "v"(hi)); return r; }
; __device__ __forceinline__ void p0_transpose_item(const float* __restrict__ W, int K, int N, bf16* __restrict__ WT, int mode, const float* __restrict__ kscale, int item, int lane) {
;     const int nblk = N / 64, kb = item / nblk, nb = item % nblk, k0 = 64 * kb, n0 = 64 * nb;
;     const float* src = W + (size_t)k0 * N + n0 + lane;
;     float v[64];
; #pragma unroll
;     for (int i = 0; i < 64; ++i) v[i] = src[(size_t)i * N];
;     if (kscale) {
; #pragma unroll
;         for (int i = 0; i < 64; ++i) v[i] *= kscale[k0 + i]; }
;     const int rbase = (mode == 0) ? n0 : (256 * (n0 >> 7) + (n0 & 127) + (mode == 2 ? 128 : 0));
;     bf16* dst = WT + (size_t)(rbase + lane) * K + k0;
; #pragma unroll
;     for (int j = 0; j < 8; ++j) { v4u o; o.x = cvtpk2(v[8 * j], v[8 * j + 1]); o.y = cvtpk2(v[8 * j + 2], v[8 * j + 3]); o.z = cvtpk2(v[8 * j + 4], v[8 * j + 5]); o.w = cvtpk2(v[8 * j + 6], v[8 * j + 7]);
;         *(v4u*)(dst + 8 * j) = o; }
; }
;     __device__ __forceinline__ void finish() const { while (nxt < NITEMS) { convert(nxt, (int)(threadIdx.x & 63)); nxt += ngw; } }
.Lp1_cv_skip_f:
	s_cmp_eq_u32 s39, 0
	s_cbranch_scc1 .Lp1_cf_skip_f
	s_waitcnt vmcnt(0)
	s_cmp_eq_u32 s9, 0
	s_cbranch_scc1 .Lp1_cf_nosc_f
	v_readlane_b32 s40, v197, 0
	v_readlane_b32 s41, v197, 1
	v_readlane_b32 s42, v197, 2
	v_readlane_b32 s43, v197, 3
	v_mul_f32_e32 v128, s40, v128
	v_readlane_b32 s40, v197, 4
	v_mul_f32_e32 v129, s41, v129
	v_readlane_b32 s41, v197, 5
	v_mul_f32_e32 v130, s42, v130
	v_readlane_b32 s42, v197, 6
	v_mul_f32_e32 v131, s43, v131
	v_readlane_b32 s43, v197, 7
	v_mul_f32_e32 v132, s40, v132
	v_readlane_b32 s40, v197, 8
	v_mul_f32_e32 v133, s41, v133
	v_readlane_b32 s41, v197, 9
	v_mul_f32_e32 v134, s42, v134
	v_readlane_b32 s42, v197, 10
	v_mul_f32_e32 v135, s43, v135
	v_readlane_b32 s43, v197, 11
	v_mul_f32_e32 v136, s40, v136
	v_readlane_b32 s40, v197, 12
	v_mul_f32_e32 v137, s41, v137
	v_readlane_b32 s41, v197, 13
	v_mul_f32_e32 v138, s42, v138
	v_readlane_b32 s42, v197, 14
	v_mul_f32_e32 v139, s43, v139
	v_readlane_b32 s43, v197, 15
	v_mul_f32_e32 v140, s40, v140
	v_readlane_b32 s40, v197, 16
	v_mul_f32_e32 v141, s41, v141
	v_readlane_b32 s41, v197, 17
	v_mul_f32_e32 v142, s42, v142
	v_readlane_b32 s42, v197, 18
	v_mul_f32_e32 v143, s43, v143
	v_readlane_b32 s43, v197, 19
	v_mul_f32_e32 v144, s40, v144
	v_readlane_b32 s40, v197, 20
	v_mul_f32_e32 v145, s41, v145
	v_readlane_b32 s41, v197, 21
	v_mul_f32_e32 v146, s42, v146
	v_readlane_b32 s42, v197, 22
	v_mul_f32_e32 v147, s43, v147
	v_readlane_b32 s43, v197, 23
	v_mul_f32_e32 v148, s40, v148
	v_readlane_b32 s40, v197, 24
	v_mul_f32_e32 v149, s41, v149
	v_readlane_b32 s41, v197, 25
	v_mul_f32_e32 v150, s42, v150
	v_readlane_b32 s42, v197, 26
	v_mul_f32_e32 v151, s43, v151
	v_readlane_b32 s43, v197, 27
	v_mul_f32_e32 v152, s40, v152
	v_readlane_b32 s40, v197, 28
	v_mul_f32_e32 v153, s41, v153
	v_readlane_b32 s41, v197, 29
	v_mul_f32_e32 v154, s42, v154
	v_readlane_b32 s42, v197, 30
	v_mul_f32_e32 v155, s43, v155
	v_readlane_b32 s43, v197, 31
	v_mul_f32_e32 v156, s40, v156
	v_readlane_b32 s40, v197, 32
	v_mul_f32_e32 v157, s41, v157
	v_readlane_b32 s41, v197, 33
	v_mul_f32_e32 v158, s42, v158
	v_readlane_b32 s42, v197, 34
	v_mul_f32_e32 v159, s43, v159
	v_readlane_b32 s43, v197, 35
	v_mul_f32_e32 v160, s40, v160
	v_readlane_b32 s40, v197, 36
	v_mul_f32_e32 v161, s41, v161
	v_readlane_b32 s41, v197, 37
	v_mul_f32_e32 v162, s42, v162
	v_readlane_b32 s42, v197, 38
	v_mul_f32_e32 v163, s43, v163
	v_readlane_b32 s43, v197, 39
	v_mul_f32_e32 v164, s40, v164
	v_readlane_b32 s40, v197, 40
	v_mul_f32_e32 v165, s41, v165
	v_readlane_b32 s41, v197, 41
	v_mul_f32_e32 v166, s42, v166
	v_readlane_b32 s42, v197, 42
	v_mul_f32_e32 v167, s43, v167
	v_readlane_b32 s43, v197, 43
	v_mul_f32_e32 v168, s40, v168
	v_readlane_b32 s40, v197, 44
	v_mul_f32_e32 v169, s41, v169
	v_readlane_b32 s41, v197, 45
	v_mul_f32_e32 v170, s42, v170
	v_readlane_b32 s42, v197, 46
	v_mul_f32_e32 v171, s43, v171
	v_readlane_b32 s43, v197, 47
	v_mul_f32_e32 v172, s40, v172
	v_readlane_b32 s40, v197, 48
	v_mul_f32_e32 v173, s41, v173
	v_readlane_b32 s41, v197, 49
	v_mul_f32_e32 v174, s42, v174
	v_readlane_b32 s42, v197, 50
	v_mul_f32_e32 v175, s43, v175
	v_readlane_b32 s43, v197, 51
	v_mul_f32_e32 v176, s40, v176
	v_readlane_b32 s40, v197, 52
	v_mul_f32_e32 v177, s41, v177
	v_readlane_b32 s41, v197, 53
	v_mul_f32_e32 v178, s42, v178
	v_readlane_b32 s42, v197, 54
	v_mul_f32_e32 v179, s43, v179
	v_readlane_b32 s43, v197, 55
	v_mul_f32_e32 v180, s40, v180
	v_readlane_b32 s40, v197, 56
	v_mul_f32_e32 v181, s41, v181
	v_readlane_b32 s41, v197, 57
	v_mul_f32_e32 v182, s42, v182
	v_readlane_b32 s42, v197, 58
	v_mul_f32_e32 v183, s43, v183
	v_readlane_b32 s43, v197, 59
	v_mul_f32_e32 v188, s40, v188
	v_readlane_b32 s40, v197, 60
	v_mul_f32_e32 v189, s41, v189
	v_readlane_b32 s41, v197, 61
	v_mul_f32_e32 v190, s42, v190
	v_readlane_b32 s42, v197, 62
	v_mul_f32_e32 v191, s43, v191
	v_readlane_b32 s43, v197, 63
	v_mul_f32_e32 v192, s40, v192
	s_nop 0
	v_mul_f32_e32 v193, s41, v193
	s_nop 0
	v_mul_f32_e32 v194, s42, v194
	s_nop 0
	v_mul_f32_e32 v195, s43, v195

; __device__ __forceinline__ unsigned xb_ld(unsigned* p)              { return __hip_atomic_load(p, __ATOMIC_RELAXED, __HIP_MEMORY_SCOPE_AGENT); }
; __device__ __forceinline__ unsigned xb_add(unsigned* p, unsigned v) { return __hip_atomic_fetch_add(p, v, __ATOMIC_RELAXED, __HIP_MEMORY_SCOPE_AGENT); }
; #define XB_SPIN(cond, bar) do { unsigned _sp = 0; while (cond) { __builtin_amdgcn_s_sleep(1); \
;     if ((++_sp & 255u) == 0u) { if (xb_ld(&(bar)[XB_TMO])) break; if (_sp > XB_SPIN_CAP) { atomicAdd(&(bar)[XB_TMO], 1u); break; } } } } while (0)
;     __device__ __forceinline__ void finish() const { while (nxt < NITEMS) { convert(nxt, (int)(threadIdx.x & 63)); nxt += ngw; } }
; #define GRID_BAR(k) do { if (IN(k) && IN((k) + 1)) xcd_barrier(bar); } while (0)
; __device__ __forceinline__ void xcd_barrier(const XcdBarrier& b) {
;     asm volatile("s_waitcnt vmcnt(0)" ::: "memory");
;     __syncthreads();
;     if (threadIdx.x == 0) {
;         unsigned* bar = b.bar;
;         __builtin_amdgcn_s_waitcnt(0);
;         unsigned nloc = b.st[0], nx = b.st[1];
;         if (nloc == 0u) { xcd_barrier_complete(bar, b.x, nloc, nx); b.st[0] = nloc; b.st[1] = nx; }
;         const unsigned old = xb_add(&bar[XB_XSUB(b.x)], 1u);
;         const unsigned gen = old / nloc;
;         if (old + 1u == (gen + 1u) * nloc) {
;             __builtin_amdgcn_fence(__ATOMIC_RELEASE, "agent");
;             asm volatile("s_waitcnt vmcnt(0)" ::: "memory");
;             const unsigned og = xb_add(&bar[XB_TOP], 1u);
;             const unsigned tg = og / nx;
;             if (og + 1u == (tg + 1u) * nx) xb_add(&bar[XB_TOPGEN], 1u);
;             else XB_SPIN(xb_ld(&bar[XB_TOPGEN]) == tg, bar);
;             __builtin_amdgcn_fence(__ATOMIC_ACQUIRE, "agent");
;             xb_add(&bar[XB_XGEN(b.x)], 1u);
;             asm volatile("s_waitcnt vmcnt(0)" ::: "memory");
;         } else {
;             XB_SPIN(xb_ld(&bar[XB_XGEN(b.x)]) == gen, bar);
;             __builtin_amdgcn_fence(__ATOMIC_ACQUIRE, "agent");
;             asm volatile("s_waitcnt vmcnt(0)" ::: "memory");
;         }
;     }
;     __syncthreads();
; }
; __global__ void __launch_bounds__(NWAVES * 64, 2) hybrid_fwd(Args args) {
;     ...
;         S.finish();
;     }
;     GRID_BAR(1);
.Lp1_cf_skip_f:
	s_branch .Lp1_fin_loop
.Lp1_fin_done:
	v_readlane_b32 s40, v253, 60
	v_readlane_b32 s41, v253, 61
	s_nop 3
	s_mov_b32 vcc_lo, s40
	s_mov_b32 vcc_hi, s41
	v_readlane_b32 s4, v253, 0
	v_readlane_b32 s5, v253, 1
	v_readlane_b32 s6, v253, 2
	v_readlane_b32 s7, v253, 3
	v_readlane_b32 s8, v253, 4
	v_readlane_b32 s9, v253, 5
	v_readlane_b32 s10, v253, 6
	v_readlane_b32 s11, v253, 7
	v_readlane_b32 s12, v253, 8
	v_readlane_b32 s13, v253, 9
	v_readlane_b32 s14, v253, 10
	v_readlane_b32 s15, v253, 11
	v_readlane_b32 s16, v253, 12
	v_readlane_b32 s17, v253, 13
	v_readlane_b32 s18, v253, 14
	v_readlane_b32 s19, v253, 15
	v_readlane_b32 s20, v253, 16
	v_readlane_b32 s21, v253, 17
	v_readlane_b32 s22, v253, 18
	v_readlane_b32 s23, v253, 19
	v_readlane_b32 s24, v253, 20
	v_readlane_b32 s25, v253, 21
	v_readlane_b32 s26, v253, 22
	v_readlane_b32 s27, v253, 23
	v_readlane_b32 s28, v253, 24
	v_readlane_b32 s29, v253, 25
	v_readlane_b32 s30, v253, 26
	v_readlane_b32 s31, v253, 27
	v_readlane_b32 s32, v253, 28
	v_readlane_b32 s33, v253, 29
	v_readlane_b32 s34, v253, 30
	v_readlane_b32 s35, v253, 31
	v_readlane_b32 s36, v253, 32
	v_readlane_b32 s37, v253, 33
	v_readlane_b32 s38, v253, 34
	v_readlane_b32 s39, v253, 35
	v_readlane_b32 s40, v253, 36
	v_readlane_b32 s41, v253, 37
	v_readlane_b32 s42, v253, 38
	v_readlane_b32 s43, v253, 39
	v_readlane_b32 s44, v253, 40
	v_readlane_b32 s45, v253, 41
	v_readlane_b32 s46, v253, 42
	v_readlane_b32 s47, v253, 43
	v_readlane_b32 s48, v253, 44
	v_readlane_b32 s49, v253, 45
	v_readlane_b32 s50, v253, 46
	v_readlane_b32 s51, v253, 47
	v_readlane_b32 s52, v253, 48
	v_readlane_b32 s53, v253, 49
	v_readlane_b32 s54, v253, 50
	v_readlane_b32 s55, v253, 51
	v_readlane_b32 s56, v253, 52
	v_readlane_b32 s57, v253, 53
	v_readlane_b32 s58, v253, 54
	v_readlane_b32 s59, v253, 55
	s_nop 7
.LBB0_154:
	v_readlane_b32 s70, v244, 10
	v_readlane_b32 s71, v244, 11
	s_cmp_gt_i32 s71, 2
	v_readlane_b32 s4, v244, 33
	s_cselect_b64 s[0:1], -1, 0
	v_readlane_b32 s5, v244, 34
	s_and_b64 s[4:5], s[4:5], s[0:1]
	v_readlane_b32 s78, v244, 31
	s_andn2_b64 vcc, exec, s[4:5]
	v_readlane_b32 s79, v244, 32
	s_cbranch_vccnz .LBB0_208
	s_waitcnt vmcnt(0)
	s_waitcnt vmcnt(0)
	s_barrier
	s_and_saveexec_b64 s[4:5], s[96:97]
	s_cbranch_execz .LBB0_207
	s_add_i32 s6, 0, 0x20fc0
	v_mov_b32_e32 v0, s6
	s_waitcnt vmcnt(0) expcnt(0) lgkmcnt(0)
	ds_read_b32 v2, v0
	s_add_i32 s6, 0, 0x20fc4
	v_mov_b32_e32 v0, s6
	ds_read_b32 v0, v0
	s_waitcnt lgkmcnt(1)
	v_cmp_ne_u32_e32 vcc, 0, v2
	s_cbranch_vccnz .LBB0_171
	v_readlane_b32 s6, v244, 4
	v_readlane_b32 s7, v244, 5
	v_readlane_b32 s8, v244, 6
	s_mul_i32 s33, s7, s8
	s_mul_i32 s33, s33, s6
	s_add_u32 s6, s76, 0x20200
	s_addc_u32 s7, s77, 0
	s_add_u32 s8, s76, 0x20400
	s_addc_u32 s9, s77, 0
	s_add_u32 s10, s76, 0x20500
	s_addc_u32 s11, s77, 0
	s_add_u32 s12, s76, 0x20600
	s_addc_u32 s13, s77, 0
	s_add_u32 s14, s76, 0x20700
	s_addc_u32 s15, s77, 0
	s_add_u32 s16, s76, 0x20800
	s_addc_u32 s17, s77, 0
	s_add_u32 s18, s76, 0x20900
	s_addc_u32 s19, s77, 0
	s_add_u32 s20, s76, 0x20a00
	s_addc_u32 s21, s77, 0
	s_add_u32 s22, s76, 0x20b00
	s_addc_u32 s23, s77, 0
	s_add_u32 s24, s76, 0x20c00
	s_addc_u32 s25, s77, 0
	s_add_u32 s26, s76, 0x20d00
	s_addc_u32 s27, s77, 0
	s_add_u32 s28, s76, 0x20e00
	s_addc_u32 s29, s77, 0
	s_add_u32 s30, s76, 0x20f00
	s_addc_u32 s31, s77, 0
	s_add_u32 s34, s76, 0x21000
	s_addc_u32 s35, s77, 0
	s_add_u32 s36, s76, 0x21100
	s_addc_u32 s37, s77, 0
	s_add_u32 s38, s76, 0x21200
	s_addc_u32 s39, s77, 0
	s_add_u32 s40, s76, 0x21300
	s_addc_u32 s41, s77, 0
	s_mov_b32 s48, 1
	v_mov_b32_e32 v16, 0
	s_branch .LBB0_159
